# nt cache policy on once-read loads: f32 weight reads in conversion tiles, EP_RES residual base reads, xb_rows and final_rows row reads
# speedup vs baseline: 1.0042x; 1.0016x over previous
; __device__ __forceinline__ unsigned cvt_pk_bf16(float lo, float hi) { f32x2 v = {lo, hi}; bf16x2_t b = __builtin_convertvector(v, bf16x2_t); return __builtin_bit_cast(unsigned, b); }
; template <int MODE> __device__ __forceinline__ void gemm_epilogue(f32x4 (&acc)[2][2][4][2], const GD& g, const pg8::Unit& u, int wr, int wc, int fr, int fq, LAS unsigned char* lds, const float (&rsv)[2][4]) {
;     ...
;     } else if constexpr (MODE == EP_RES) {
;         const float* base = g.f0; float* out = (float*)g.o0; bf16_t* xb = (bf16_t*)g.o1; float* ssq = (float*)g.f1;
;         const int col0 = u.pn * 256 + wc * 32 + 4 * fq; const int rz = (u.z / g.nz2) * g.ro1;
; #pragma unroll
;         for (int ai = 0; ai < 2; ++ai)
; #pragma unroll
;             for (int m = 0; m < 4; ++m) { const size_t off = (size_t)(rz + rt + ai * 128 + m * 16) * DM + col0;
;                 float ss = 0.f;
; #pragma unroll
;                 for (int bj = 0; bj < 2; ++bj)
; #pragma unroll
;                     for (int n = 0; n < 2; ++n) { const f32x4 bs = *(const f32x4*)(base + off + bj * 128 + n * 16); const f32x4 y = bs + acc[ai][bj][m][n]; *(f32x4*)(out + off + bj * 128 + n * 16) = y;
;                         ss += (y[0] * y[0] + y[1] * y[1]) + (y[2] * y[2] + y[3] * y[3]);
;                         u32x2 w; w.x = cvt_pk_bf16(y[0], y[1]); w.y = cvt_pk_bf16(y[2], y[3]); if (xb) *(u32x2*)(xb + off + bj * 128 + n * 16) = w; }
;                 ss += __shfl_xor(ss, 16); ss += __shfl_xor(ss, 32);
;                 if (fq == 0) __hip_atomic_fetch_add(ssq + rz + rt + ai * 128 + m * 16, ss, __ATOMIC_RELAXED, __HIP_MEMORY_SCOPE_AGENT); }
.LBB0_196:
	s_abs_i32 s3, s38
	s_mul_hi_u32 s8, s3, s0
	s_mul_i32 s9, s8, s1
	s_ashr_i32 s2, s38, 31
	s_sub_i32 s3, s3, s9
	s_xor_b32 s2, s2, s52
	s_add_i32 s9, s8, 1
	s_sub_i32 s12, s3, s1
	s_cmp_ge_u32 s3, s1
	s_cselect_b32 s8, s9, s8
	s_cselect_b32 s3, s12, s3
	s_add_i32 s9, s8, 1
	s_cmp_ge_u32 s3, s1
	s_cselect_b32 s3, s9, s8
	s_xor_b32 s3, s3, s2
	s_sub_i32 s2, s3, s2
	v_readlane_b32 s3, v254, 59
	v_readlane_b32 s8, v254, 42
	v_lshl_add_u32 v144, s56, 8, v154
	s_mul_i32 s2, s2, s3
	v_readlane_b32 s9, v254, 43
	v_add_u32_e32 v144, s2, v144
	v_lshl_or_b32 v145, s53, 8, v164
	v_readlane_b32 s2, v254, 48
	v_readlane_b32 s3, v254, 49
	v_lshlrev_b32_e32 v146, 2, v144
	v_lshl_add_u32 v143, v144, 11, v145
	v_and_b32_e32 v149, 64, v252
	v_lshlrev_b32_e32 v147, 1, v143
	v_lshlrev_b32_e32 v143, 2, v143
	v_xor_b32_e32 v1, 16, v252
	v_add_u32_e32 v149, 64, v149
	v_xor_b32_e32 v142, 32, v252
	v_mov_b32_e32 v148, v143
	v_cmp_lt_i32_e32 vcc, v1, v149
	s_nop 1
	v_cndmask_b32_e32 v1, v252, v1, vcc
	v_cmp_lt_i32_e32 vcc, v142, v149
	v_lshlrev_b32_e32 v1, 2, v1
	s_nop 0
	v_cndmask_b32_e32 v142, v252, v142, vcc
	v_lshlrev_b32_e32 v142, 2, v142
	s_and_b64 vcc, exec, s[62:63]
	s_cbranch_vccz .Lres_noxb
	global_load_dwordx4 v[168:171], v143, s[2:3] offset:0 nt
	global_load_dwordx4 v[172:175], v143, s[2:3] offset:64 nt
	global_load_dwordx4 v[176:179], v143, s[2:3] offset:512 nt
	global_load_dwordx4 v[180:183], v143, s[2:3] offset:576 nt
	v_add_u32_e32 v143, 0x20000, v143
	global_load_dwordx4 v[184:187], v143, s[2:3] offset:0 nt
	global_load_dwordx4 v[188:191], v143, s[2:3] offset:64 nt
	global_load_dwordx4 v[196:199], v143, s[2:3] offset:512 nt
	global_load_dwordx4 v[204:207], v143, s[2:3] offset:576 nt
	v_add_u32_e32 v143, 0x20000, v143
	global_load_dwordx4 v[220:223], v143, s[2:3] offset:0 nt
	global_load_dwordx4 v[224:227], v143, s[2:3] offset:64 nt
	global_load_dwordx4 v[228:231], v143, s[2:3] offset:512 nt
	global_load_dwordx4 v[232:235], v143, s[2:3] offset:576 nt
	s_waitcnt vmcnt(8)
	v_pk_add_f32 v[128:129], v[128:129], v[170:171]
	v_pk_add_f32 v[126:127], v[126:127], v[168:169]
	v_pk_add_f32 v[124:125], v[124:125], v[174:175]
	v_pk_add_f32 v[122:123], v[122:123], v[172:173]
	v_pk_add_f32 v[120:121], v[120:121], v[178:179]
	v_pk_add_f32 v[118:119], v[118:119], v[176:177]
	v_pk_add_f32 v[116:117], v[116:117], v[182:183]
	v_pk_add_f32 v[114:115], v[114:115], v[180:181]
	global_store_dwordx4 v148, v[126:129], s[8:9] offset:0
	global_store_dwordx4 v148, v[122:125], s[8:9] offset:64
	global_store_dwordx4 v148, v[118:121], s[8:9] offset:512
	global_store_dwordx4 v148, v[114:117], s[8:9] offset:576
	v_cvt_pk_bf16_f32 v168, v126, v127
	v_cvt_pk_bf16_f32 v169, v128, v129
	v_cvt_pk_bf16_f32 v172, v122, v123
	v_cvt_pk_bf16_f32 v173, v124, v125
	v_cvt_pk_bf16_f32 v176, v118, v119
	v_cvt_pk_bf16_f32 v177, v120, v121
	v_cvt_pk_bf16_f32 v180, v114, v115
	v_cvt_pk_bf16_f32 v181, v116, v117
	global_store_dwordx2 v147, v[168:169], s[36:37] offset:0
	global_store_dwordx2 v147, v[172:173], s[36:37] offset:32
	global_store_dwordx2 v147, v[176:177], s[36:37] offset:256
	global_store_dwordx2 v147, v[180:181], s[36:37] offset:288
	v_mul_f32_e32 v150, v127, v127
	v_mul_f32_e32 v151, v129, v129
	v_fmac_f32_e32 v150, v126, v126
	v_fmac_f32_e32 v151, v128, v128
	v_add_f32_e32 v150, v150, v151
	v_mul_f32_e32 v152, v123, v123
	v_mul_f32_e32 v153, v125, v125
	v_fmac_f32_e32 v152, v122, v122
	v_fmac_f32_e32 v153, v124, v124
	v_add_f32_e32 v152, v152, v153
	v_add_f32_e32 v150, v150, v152
	v_mul_f32_e32 v152, v119, v119
	v_mul_f32_e32 v153, v121, v121
	v_fmac_f32_e32 v152, v118, v118
	v_fmac_f32_e32 v153, v120, v120
	v_add_f32_e32 v152, v152, v153
	v_add_f32_e32 v150, v150, v152
	v_mul_f32_e32 v152, v115, v115
	v_mul_f32_e32 v153, v117, v117
	v_fmac_f32_e32 v152, v114, v114
	v_fmac_f32_e32 v153, v116, v116
	v_add_f32_e32 v152, v152, v153
	v_add_f32_e32 v150, v150, v152
	ds_bpermute_b32 v192, v1, v150
	v_add_u32_e32 v143, 0x20000, v143
	global_load_dwordx4 v[168:171], v143, s[2:3] offset:0 nt
	global_load_dwordx4 v[172:175], v143, s[2:3] offset:64 nt
	global_load_dwordx4 v[176:179], v143, s[2:3] offset:512 nt
	global_load_dwordx4 v[180:183], v143, s[2:3] offset:576 nt
	s_waitcnt lgkmcnt(0)
	v_add_f32_e32 v150, v150, v192
	ds_bpermute_b32 v192, v142, v150
	v_add_u32_e32 v148, 0x20000, v148
	v_add_u32_e32 v147, 0x10000, v147
	s_and_saveexec_b64 s[12:13], s[6:7]
	s_waitcnt lgkmcnt(0)
	v_add_f32_e32 v150, v150, v192
	global_atomic_add_f32 v146, v150, s[70:71] offset:0
	s_mov_b64 exec, s[12:13]
	s_waitcnt vmcnt(17)
; __device__ __forceinline__ unsigned cvt_pk_bf16(float lo, float hi) { f32x2 v = {lo, hi}; bf16x2_t b = __builtin_convertvector(v, bf16x2_t); return __builtin_bit_cast(unsigned, b); }
; template <int MODE> __device__ __forceinline__ void gemm_epilogue(f32x4 (&acc)[2][2][4][2], const GD& g, const pg8::Unit& u, int wr, int wc, int fr, int fq, LAS unsigned char* lds, const float (&rsv)[2][4]) {
;     ...
;     } else if constexpr (MODE == EP_RES) {
;         const float* base = g.f0; float* out = (float*)g.o0; bf16_t* xb = (bf16_t*)g.o1; float* ssq = (float*)g.f1;
;         const int col0 = u.pn * 256 + wc * 32 + 4 * fq; const int rz = (u.z / g.nz2) * g.ro1;
; #pragma unroll
;         for (int ai = 0; ai < 2; ++ai)
; #pragma unroll
;             for (int m = 0; m < 4; ++m) { const size_t off = (size_t)(rz + rt + ai * 128 + m * 16) * DM + col0;
;                 float ss = 0.f;
; #pragma unroll
;                 for (int bj = 0; bj < 2; ++bj)
; #pragma unroll
;                     for (int n = 0; n < 2; ++n) { const f32x4 bs = *(const f32x4*)(base + off + bj * 128 + n * 16); const f32x4 y = bs + acc[ai][bj][m][n]; *(f32x4*)(out + off + bj * 128 + n * 16) = y;
;                         ss += (y[0] * y[0] + y[1] * y[1]) + (y[2] * y[2] + y[3] * y[3]);
;                         u32x2 w; w.x = cvt_pk_bf16(y[0], y[1]); w.y = cvt_pk_bf16(y[2], y[3]); if (xb) *(u32x2*)(xb + off + bj * 128 + n * 16) = w; }
;                 ss += __shfl_xor(ss, 16); ss += __shfl_xor(ss, 32);
;                 if (fq == 0) __hip_atomic_fetch_add(ssq + rz + rt + ai * 128 + m * 16, ss, __ATOMIC_RELAXED, __HIP_MEMORY_SCOPE_AGENT); }
	v_pk_add_f32 v[112:113], v[112:113], v[186:187]
	v_pk_add_f32 v[110:111], v[110:111], v[184:185]
	v_pk_add_f32 v[108:109], v[108:109], v[190:191]
	v_pk_add_f32 v[106:107], v[106:107], v[188:189]
	v_pk_add_f32 v[104:105], v[104:105], v[198:199]
	v_pk_add_f32 v[102:103], v[102:103], v[196:197]
	v_pk_add_f32 v[100:101], v[100:101], v[206:207]
	v_pk_add_f32 v[98:99], v[98:99], v[204:205]
	global_store_dwordx4 v148, v[110:113], s[8:9] offset:0
	global_store_dwordx4 v148, v[106:109], s[8:9] offset:64
	global_store_dwordx4 v148, v[102:105], s[8:9] offset:512
	global_store_dwordx4 v148, v[98:101], s[8:9] offset:576
	v_cvt_pk_bf16_f32 v184, v110, v111
	v_cvt_pk_bf16_f32 v185, v112, v113
	v_cvt_pk_bf16_f32 v188, v106, v107
	v_cvt_pk_bf16_f32 v189, v108, v109
	v_cvt_pk_bf16_f32 v196, v102, v103
	v_cvt_pk_bf16_f32 v197, v104, v105
	v_cvt_pk_bf16_f32 v204, v98, v99
	v_cvt_pk_bf16_f32 v205, v100, v101
	global_store_dwordx2 v147, v[184:185], s[36:37] offset:0
	global_store_dwordx2 v147, v[188:189], s[36:37] offset:32
	global_store_dwordx2 v147, v[196:197], s[36:37] offset:256
	global_store_dwordx2 v147, v[204:205], s[36:37] offset:288
	v_mul_f32_e32 v150, v111, v111
	v_mul_f32_e32 v151, v113, v113
	v_fmac_f32_e32 v150, v110, v110
	v_fmac_f32_e32 v151, v112, v112
	v_add_f32_e32 v150, v150, v151
	v_mul_f32_e32 v152, v107, v107
	v_mul_f32_e32 v153, v109, v109
	v_fmac_f32_e32 v152, v106, v106
	v_fmac_f32_e32 v153, v108, v108
	v_add_f32_e32 v152, v152, v153
	v_add_f32_e32 v150, v150, v152
	v_mul_f32_e32 v152, v103, v103
	v_mul_f32_e32 v153, v105, v105
	v_fmac_f32_e32 v152, v102, v102
	v_fmac_f32_e32 v153, v104, v104
	v_add_f32_e32 v152, v152, v153
	v_add_f32_e32 v150, v150, v152
	v_mul_f32_e32 v152, v99, v99
	v_mul_f32_e32 v153, v101, v101
	v_fmac_f32_e32 v152, v98, v98
	v_fmac_f32_e32 v153, v100, v100
	v_add_f32_e32 v152, v152, v153
	v_add_f32_e32 v150, v150, v152
	ds_bpermute_b32 v192, v1, v150
	v_add_u32_e32 v143, 0xa0000, v143
	global_load_dwordx4 v[184:187], v143, s[2:3] offset:0 nt
	global_load_dwordx4 v[188:191], v143, s[2:3] offset:64 nt
	global_load_dwordx4 v[196:199], v143, s[2:3] offset:512 nt
	global_load_dwordx4 v[204:207], v143, s[2:3] offset:576 nt
	s_waitcnt lgkmcnt(0)
	v_add_f32_e32 v150, v150, v192
	ds_bpermute_b32 v192, v142, v150
	v_add_u32_e32 v148, 0x20000, v148
	v_add_u32_e32 v147, 0x10000, v147
	s_and_saveexec_b64 s[12:13], s[6:7]
	s_waitcnt lgkmcnt(0)
	v_add_f32_e32 v150, v150, v192
	global_atomic_add_f32 v146, v150, s[70:71] offset:64
	s_mov_b64 exec, s[12:13]
	s_waitcnt vmcnt(26)
	v_pk_add_f32 v[96:97], v[96:97], v[222:223]
	v_pk_add_f32 v[94:95], v[94:95], v[220:221]
	v_pk_add_f32 v[92:93], v[92:93], v[226:227]
	v_pk_add_f32 v[90:91], v[90:91], v[224:225]
	v_pk_add_f32 v[88:89], v[88:89], v[230:231]
	v_pk_add_f32 v[86:87], v[86:87], v[228:229]
	v_pk_add_f32 v[84:85], v[84:85], v[234:235]
	v_pk_add_f32 v[82:83], v[82:83], v[232:233]
	global_store_dwordx4 v148, v[94:97], s[8:9] offset:0
	global_store_dwordx4 v148, v[90:93], s[8:9] offset:64
	global_store_dwordx4 v148, v[86:89], s[8:9] offset:512
	global_store_dwordx4 v148, v[82:85], s[8:9] offset:576
	v_cvt_pk_bf16_f32 v220, v94, v95
	v_cvt_pk_bf16_f32 v221, v96, v97
	v_cvt_pk_bf16_f32 v224, v90, v91
	v_cvt_pk_bf16_f32 v225, v92, v93
	v_cvt_pk_bf16_f32 v228, v86, v87
	v_cvt_pk_bf16_f32 v229, v88, v89
	v_cvt_pk_bf16_f32 v232, v82, v83
	v_cvt_pk_bf16_f32 v233, v84, v85
	global_store_dwordx2 v147, v[220:221], s[36:37] offset:0
	global_store_dwordx2 v147, v[224:225], s[36:37] offset:32
	global_store_dwordx2 v147, v[228:229], s[36:37] offset:256
	global_store_dwordx2 v147, v[232:233], s[36:37] offset:288
	v_mul_f32_e32 v150, v95, v95
	v_mul_f32_e32 v151, v97, v97
	v_fmac_f32_e32 v150, v94, v94
	v_fmac_f32_e32 v151, v96, v96
	v_add_f32_e32 v150, v150, v151
	v_mul_f32_e32 v152, v91, v91
	v_mul_f32_e32 v153, v93, v93
	v_fmac_f32_e32 v152, v90, v90
	v_fmac_f32_e32 v153, v92, v92
	v_add_f32_e32 v152, v152, v153
	v_add_f32_e32 v150, v150, v152
	v_mul_f32_e32 v152, v87, v87
	v_mul_f32_e32 v153, v89, v89
	v_fmac_f32_e32 v152, v86, v86
	v_fmac_f32_e32 v153, v88, v88
	v_add_f32_e32 v152, v152, v153
	v_add_f32_e32 v150, v150, v152
	v_mul_f32_e32 v152, v83, v83
	v_mul_f32_e32 v153, v85, v85
	v_fmac_f32_e32 v152, v82, v82
	v_fmac_f32_e32 v153, v84, v84
	v_add_f32_e32 v152, v152, v153
	v_add_f32_e32 v150, v150, v152
	ds_bpermute_b32 v192, v1, v150
	v_add_u32_e32 v143, 0x20000, v143
	global_load_dwordx4 v[220:223], v143, s[2:3] offset:0 nt
	global_load_dwordx4 v[224:227], v143, s[2:3] offset:64 nt
	global_load_dwordx4 v[228:231], v143, s[2:3] offset:512 nt
	global_load_dwordx4 v[232:235], v143, s[2:3] offset:576 nt
	s_waitcnt lgkmcnt(0)
	v_add_f32_e32 v150, v150, v192
	ds_bpermute_b32 v192, v142, v150
	v_add_u32_e32 v148, 0x20000, v148
	v_add_u32_e32 v147, 0x10000, v147
	s_and_saveexec_b64 s[12:13], s[6:7]
	s_waitcnt lgkmcnt(0)
	v_add_f32_e32 v150, v150, v192
	global_atomic_add_f32 v146, v150, s[70:71] offset:128
	s_mov_b64 exec, s[12:13]
	s_waitcnt vmcnt(27)
; __device__ __forceinline__ unsigned cvt_pk_bf16(float lo, float hi) { f32x2 v = {lo, hi}; bf16x2_t b = __builtin_convertvector(v, bf16x2_t); return __builtin_bit_cast(unsigned, b); }
; template <int MODE> __device__ __forceinline__ void gemm_epilogue(f32x4 (&acc)[2][2][4][2], const GD& g, const pg8::Unit& u, int wr, int wc, int fr, int fq, LAS unsigned char* lds, const float (&rsv)[2][4]) {
;     ...
;     } else if constexpr (MODE == EP_RES) {
;         const float* base = g.f0; float* out = (float*)g.o0; bf16_t* xb = (bf16_t*)g.o1; float* ssq = (float*)g.f1;
;         const int col0 = u.pn * 256 + wc * 32 + 4 * fq; const int rz = (u.z / g.nz2) * g.ro1;
; #pragma unroll
;         for (int ai = 0; ai < 2; ++ai)
; #pragma unroll
;             for (int m = 0; m < 4; ++m) { const size_t off = (size_t)(rz + rt + ai * 128 + m * 16) * DM + col0;
;                 float ss = 0.f;
; #pragma unroll
;                 for (int bj = 0; bj < 2; ++bj)
; #pragma unroll
;                     for (int n = 0; n < 2; ++n) { const f32x4 bs = *(const f32x4*)(base + off + bj * 128 + n * 16); const f32x4 y = bs + acc[ai][bj][m][n]; *(f32x4*)(out + off + bj * 128 + n * 16) = y;
;                         ss += (y[0] * y[0] + y[1] * y[1]) + (y[2] * y[2] + y[3] * y[3]);
;                         u32x2 w; w.x = cvt_pk_bf16(y[0], y[1]); w.y = cvt_pk_bf16(y[2], y[3]); if (xb) *(u32x2*)(xb + off + bj * 128 + n * 16) = w; }
;                 ss += __shfl_xor(ss, 16); ss += __shfl_xor(ss, 32);
;                 if (fq == 0) __hip_atomic_fetch_add(ssq + rz + rt + ai * 128 + m * 16, ss, __ATOMIC_RELAXED, __HIP_MEMORY_SCOPE_AGENT); }
	v_pk_add_f32 v[80:81], v[80:81], v[170:171]
	v_pk_add_f32 v[78:79], v[78:79], v[168:169]
	v_pk_add_f32 v[76:77], v[76:77], v[174:175]
	v_pk_add_f32 v[74:75], v[74:75], v[172:173]
	v_pk_add_f32 v[72:73], v[72:73], v[178:179]
	v_pk_add_f32 v[70:71], v[70:71], v[176:177]
	v_pk_add_f32 v[68:69], v[68:69], v[182:183]
	v_pk_add_f32 v[66:67], v[66:67], v[180:181]
	global_store_dwordx4 v148, v[78:81], s[8:9] offset:0
	global_store_dwordx4 v148, v[74:77], s[8:9] offset:64
	global_store_dwordx4 v148, v[70:73], s[8:9] offset:512
	global_store_dwordx4 v148, v[66:69], s[8:9] offset:576
	v_cvt_pk_bf16_f32 v168, v78, v79
	v_cvt_pk_bf16_f32 v169, v80, v81
	v_cvt_pk_bf16_f32 v172, v74, v75
	v_cvt_pk_bf16_f32 v173, v76, v77
	v_cvt_pk_bf16_f32 v176, v70, v71
	v_cvt_pk_bf16_f32 v177, v72, v73
	v_cvt_pk_bf16_f32 v180, v66, v67
	v_cvt_pk_bf16_f32 v181, v68, v69
	global_store_dwordx2 v147, v[168:169], s[36:37] offset:0
	global_store_dwordx2 v147, v[172:173], s[36:37] offset:32
	global_store_dwordx2 v147, v[176:177], s[36:37] offset:256
	global_store_dwordx2 v147, v[180:181], s[36:37] offset:288
	v_mul_f32_e32 v150, v79, v79
	v_mul_f32_e32 v151, v81, v81
	v_fmac_f32_e32 v150, v78, v78
	v_fmac_f32_e32 v151, v80, v80
	v_add_f32_e32 v150, v150, v151
	v_mul_f32_e32 v152, v75, v75
	v_mul_f32_e32 v153, v77, v77
	v_fmac_f32_e32 v152, v74, v74
	v_fmac_f32_e32 v153, v76, v76
	v_add_f32_e32 v152, v152, v153
	v_add_f32_e32 v150, v150, v152
	v_mul_f32_e32 v152, v71, v71
	v_mul_f32_e32 v153, v73, v73
	v_fmac_f32_e32 v152, v70, v70
	v_fmac_f32_e32 v153, v72, v72
	v_add_f32_e32 v152, v152, v153
	v_add_f32_e32 v150, v150, v152
	v_mul_f32_e32 v152, v67, v67
	v_mul_f32_e32 v153, v69, v69
	v_fmac_f32_e32 v152, v66, v66
	v_fmac_f32_e32 v153, v68, v68
	v_add_f32_e32 v152, v152, v153
	v_add_f32_e32 v150, v150, v152
	ds_bpermute_b32 v192, v1, v150
	v_add_u32_e32 v143, 0x20000, v143
	global_load_dwordx4 v[168:171], v143, s[2:3] offset:0 nt
	global_load_dwordx4 v[172:175], v143, s[2:3] offset:64 nt
	global_load_dwordx4 v[176:179], v143, s[2:3] offset:512 nt
	global_load_dwordx4 v[180:183], v143, s[2:3] offset:576 nt
	s_waitcnt lgkmcnt(0)
	v_add_f32_e32 v150, v150, v192
	ds_bpermute_b32 v192, v142, v150
	v_add_u32_e32 v148, 0xa0000, v148
	v_add_u32_e32 v147, 0x50000, v147
	s_and_saveexec_b64 s[12:13], s[6:7]
	s_waitcnt lgkmcnt(0)
	v_add_f32_e32 v150, v150, v192
	global_atomic_add_f32 v146, v150, s[70:71] offset:192
	s_mov_b64 exec, s[12:13]
	s_waitcnt vmcnt(27)
	v_pk_add_f32 v[64:65], v[64:65], v[186:187]
	v_pk_add_f32 v[62:63], v[62:63], v[184:185]
	v_pk_add_f32 v[60:61], v[60:61], v[190:191]
	v_pk_add_f32 v[58:59], v[58:59], v[188:189]
	v_pk_add_f32 v[56:57], v[56:57], v[198:199]
	v_pk_add_f32 v[54:55], v[54:55], v[196:197]
	v_pk_add_f32 v[52:53], v[52:53], v[206:207]
	v_pk_add_f32 v[50:51], v[50:51], v[204:205]
	global_store_dwordx4 v148, v[62:65], s[8:9] offset:0
	global_store_dwordx4 v148, v[58:61], s[8:9] offset:64
	global_store_dwordx4 v148, v[54:57], s[8:9] offset:512
	global_store_dwordx4 v148, v[50:53], s[8:9] offset:576
	v_cvt_pk_bf16_f32 v184, v62, v63
	v_cvt_pk_bf16_f32 v185, v64, v65
	v_cvt_pk_bf16_f32 v188, v58, v59
	v_cvt_pk_bf16_f32 v189, v60, v61
	v_cvt_pk_bf16_f32 v196, v54, v55
	v_cvt_pk_bf16_f32 v197, v56, v57
	v_cvt_pk_bf16_f32 v204, v50, v51
	v_cvt_pk_bf16_f32 v205, v52, v53
	global_store_dwordx2 v147, v[184:185], s[36:37] offset:0
	global_store_dwordx2 v147, v[188:189], s[36:37] offset:32
	global_store_dwordx2 v147, v[196:197], s[36:37] offset:256
	global_store_dwordx2 v147, v[204:205], s[36:37] offset:288
	v_mul_f32_e32 v150, v63, v63
	v_mul_f32_e32 v151, v65, v65
	v_fmac_f32_e32 v150, v62, v62
	v_fmac_f32_e32 v151, v64, v64
	v_add_f32_e32 v150, v150, v151
	v_mul_f32_e32 v152, v59, v59
	v_mul_f32_e32 v153, v61, v61
	v_fmac_f32_e32 v152, v58, v58
	v_fmac_f32_e32 v153, v60, v60
	v_add_f32_e32 v152, v152, v153
	v_add_f32_e32 v150, v150, v152
	v_mul_f32_e32 v152, v55, v55
	v_mul_f32_e32 v153, v57, v57
	v_fmac_f32_e32 v152, v54, v54
	v_fmac_f32_e32 v153, v56, v56
	v_add_f32_e32 v152, v152, v153
	v_add_f32_e32 v150, v150, v152
	v_mul_f32_e32 v152, v51, v51
	v_mul_f32_e32 v153, v53, v53
	v_fmac_f32_e32 v152, v50, v50
	v_fmac_f32_e32 v153, v52, v52
	v_add_f32_e32 v152, v152, v153
	v_add_f32_e32 v150, v150, v152
	ds_bpermute_b32 v192, v1, v150
	v_add_u32_e32 v143, 0x20000, v143
	global_load_dwordx4 v[184:187], v143, s[2:3] offset:0 nt
	global_load_dwordx4 v[188:191], v143, s[2:3] offset:64 nt
	global_load_dwordx4 v[196:199], v143, s[2:3] offset:512 nt
	global_load_dwordx4 v[204:207], v143, s[2:3] offset:576 nt
	s_waitcnt lgkmcnt(0)
	v_add_f32_e32 v150, v150, v192
	ds_bpermute_b32 v192, v142, v150
	v_add_u32_e32 v148, 0x20000, v148
	v_add_u32_e32 v147, 0x10000, v147
	s_and_saveexec_b64 s[12:13], s[6:7]
	s_waitcnt lgkmcnt(0)
	v_add_f32_e32 v150, v150, v192
	global_atomic_add_f32 v146, v150, s[70:71] offset:512
	s_mov_b64 exec, s[12:13]
	s_waitcnt vmcnt(27)
; __device__ __forceinline__ unsigned cvt_pk_bf16(float lo, float hi) { f32x2 v = {lo, hi}; bf16x2_t b = __builtin_convertvector(v, bf16x2_t); return __builtin_bit_cast(unsigned, b); }
; template <int MODE> __device__ __forceinline__ void gemm_epilogue(f32x4 (&acc)[2][2][4][2], const GD& g, const pg8::Unit& u, int wr, int wc, int fr, int fq, LAS unsigned char* lds, const float (&rsv)[2][4]) {
;     ...
;     } else if constexpr (MODE == EP_RES) {
;         const float* base = g.f0; float* out = (float*)g.o0; bf16_t* xb = (bf16_t*)g.o1; float* ssq = (float*)g.f1;
;         const int col0 = u.pn * 256 + wc * 32 + 4 * fq; const int rz = (u.z / g.nz2) * g.ro1;
; #pragma unroll
;         for (int ai = 0; ai < 2; ++ai)
; #pragma unroll
;             for (int m = 0; m < 4; ++m) { const size_t off = (size_t)(rz + rt + ai * 128 + m * 16) * DM + col0;
;                 float ss = 0.f;
; #pragma unroll
;                 for (int bj = 0; bj < 2; ++bj)
; #pragma unroll
;                     for (int n = 0; n < 2; ++n) { const f32x4 bs = *(const f32x4*)(base + off + bj * 128 + n * 16); const f32x4 y = bs + acc[ai][bj][m][n]; *(f32x4*)(out + off + bj * 128 + n * 16) = y;
;                         ss += (y[0] * y[0] + y[1] * y[1]) + (y[2] * y[2] + y[3] * y[3]);
;                         u32x2 w; w.x = cvt_pk_bf16(y[0], y[1]); w.y = cvt_pk_bf16(y[2], y[3]); if (xb) *(u32x2*)(xb + off + bj * 128 + n * 16) = w; }
;                 ss += __shfl_xor(ss, 16); ss += __shfl_xor(ss, 32);
;                 if (fq == 0) __hip_atomic_fetch_add(ssq + rz + rt + ai * 128 + m * 16, ss, __ATOMIC_RELAXED, __HIP_MEMORY_SCOPE_AGENT); }
	v_pk_add_f32 v[48:49], v[48:49], v[222:223]
	v_pk_add_f32 v[46:47], v[46:47], v[220:221]
	v_pk_add_f32 v[44:45], v[44:45], v[226:227]
	v_pk_add_f32 v[42:43], v[42:43], v[224:225]
	v_pk_add_f32 v[40:41], v[40:41], v[230:231]
	v_pk_add_f32 v[38:39], v[38:39], v[228:229]
	v_pk_add_f32 v[36:37], v[36:37], v[234:235]
	v_pk_add_f32 v[34:35], v[34:35], v[232:233]
	global_store_dwordx4 v148, v[46:49], s[8:9] offset:0
	global_store_dwordx4 v148, v[42:45], s[8:9] offset:64
	global_store_dwordx4 v148, v[38:41], s[8:9] offset:512
	global_store_dwordx4 v148, v[34:37], s[8:9] offset:576
	v_cvt_pk_bf16_f32 v220, v46, v47
	v_cvt_pk_bf16_f32 v221, v48, v49
	v_cvt_pk_bf16_f32 v224, v42, v43
	v_cvt_pk_bf16_f32 v225, v44, v45
	v_cvt_pk_bf16_f32 v228, v38, v39
	v_cvt_pk_bf16_f32 v229, v40, v41
	v_cvt_pk_bf16_f32 v232, v34, v35
	v_cvt_pk_bf16_f32 v233, v36, v37
	global_store_dwordx2 v147, v[220:221], s[36:37] offset:0
	global_store_dwordx2 v147, v[224:225], s[36:37] offset:32
	global_store_dwordx2 v147, v[228:229], s[36:37] offset:256
	global_store_dwordx2 v147, v[232:233], s[36:37] offset:288
	v_mul_f32_e32 v150, v47, v47
	v_mul_f32_e32 v151, v49, v49
	v_fmac_f32_e32 v150, v46, v46
	v_fmac_f32_e32 v151, v48, v48
	v_add_f32_e32 v150, v150, v151
	v_mul_f32_e32 v152, v43, v43
	v_mul_f32_e32 v153, v45, v45
	v_fmac_f32_e32 v152, v42, v42
	v_fmac_f32_e32 v153, v44, v44
	v_add_f32_e32 v152, v152, v153
	v_add_f32_e32 v150, v150, v152
	v_mul_f32_e32 v152, v39, v39
	v_mul_f32_e32 v153, v41, v41
	v_fmac_f32_e32 v152, v38, v38
	v_fmac_f32_e32 v153, v40, v40
	v_add_f32_e32 v152, v152, v153
	v_add_f32_e32 v150, v150, v152
	v_mul_f32_e32 v152, v35, v35
	v_mul_f32_e32 v153, v37, v37
	v_fmac_f32_e32 v152, v34, v34
	v_fmac_f32_e32 v153, v36, v36
	v_add_f32_e32 v152, v152, v153
	v_add_f32_e32 v150, v150, v152
	ds_bpermute_b32 v192, v1, v150
	s_waitcnt lgkmcnt(0)
	v_add_f32_e32 v150, v150, v192
	ds_bpermute_b32 v192, v142, v150
	v_add_u32_e32 v148, 0x20000, v148
	v_add_u32_e32 v147, 0x10000, v147
	s_and_saveexec_b64 s[12:13], s[6:7]
	s_waitcnt lgkmcnt(0)
	v_add_f32_e32 v150, v150, v192
	global_atomic_add_f32 v146, v150, s[70:71] offset:576
	s_mov_b64 exec, s[12:13]
	s_waitcnt vmcnt(23)
	v_pk_add_f32 v[32:33], v[32:33], v[170:171]
	v_pk_add_f32 v[30:31], v[30:31], v[168:169]
	v_pk_add_f32 v[28:29], v[28:29], v[174:175]
	v_pk_add_f32 v[26:27], v[26:27], v[172:173]
	v_pk_add_f32 v[24:25], v[24:25], v[178:179]
	v_pk_add_f32 v[22:23], v[22:23], v[176:177]
	v_pk_add_f32 v[20:21], v[20:21], v[182:183]
	v_pk_add_f32 v[18:19], v[18:19], v[180:181]
	global_store_dwordx4 v148, v[30:33], s[8:9] offset:0
	global_store_dwordx4 v148, v[26:29], s[8:9] offset:64
	global_store_dwordx4 v148, v[22:25], s[8:9] offset:512
	global_store_dwordx4 v148, v[18:21], s[8:9] offset:576
	v_cvt_pk_bf16_f32 v168, v30, v31
	v_cvt_pk_bf16_f32 v169, v32, v33
	v_cvt_pk_bf16_f32 v172, v26, v27
	v_cvt_pk_bf16_f32 v173, v28, v29
	v_cvt_pk_bf16_f32 v176, v22, v23
	v_cvt_pk_bf16_f32 v177, v24, v25
	v_cvt_pk_bf16_f32 v180, v18, v19
	v_cvt_pk_bf16_f32 v181, v20, v21
	global_store_dwordx2 v147, v[168:169], s[36:37] offset:0
	global_store_dwordx2 v147, v[172:173], s[36:37] offset:32
	global_store_dwordx2 v147, v[176:177], s[36:37] offset:256
	global_store_dwordx2 v147, v[180:181], s[36:37] offset:288
	v_mul_f32_e32 v150, v31, v31
	v_mul_f32_e32 v151, v33, v33
	v_fmac_f32_e32 v150, v30, v30
	v_fmac_f32_e32 v151, v32, v32
	v_add_f32_e32 v150, v150, v151
	v_mul_f32_e32 v152, v27, v27
	v_mul_f32_e32 v153, v29, v29
	v_fmac_f32_e32 v152, v26, v26
	v_fmac_f32_e32 v153, v28, v28
	v_add_f32_e32 v152, v152, v153
	v_add_f32_e32 v150, v150, v152
	v_mul_f32_e32 v152, v23, v23
	v_mul_f32_e32 v153, v25, v25
	v_fmac_f32_e32 v152, v22, v22
	v_fmac_f32_e32 v153, v24, v24
	v_add_f32_e32 v152, v152, v153
	v_add_f32_e32 v150, v150, v152
	v_mul_f32_e32 v152, v19, v19
	v_mul_f32_e32 v153, v21, v21
	v_fmac_f32_e32 v152, v18, v18
	v_fmac_f32_e32 v153, v20, v20
	v_add_f32_e32 v152, v152, v153
	v_add_f32_e32 v150, v150, v152
	ds_bpermute_b32 v192, v1, v150
	s_waitcnt lgkmcnt(0)
	v_add_f32_e32 v150, v150, v192
	ds_bpermute_b32 v192, v142, v150
	v_add_u32_e32 v148, 0x20000, v148
	v_add_u32_e32 v147, 0x10000, v147
	s_and_saveexec_b64 s[12:13], s[6:7]
	s_waitcnt lgkmcnt(0)
	v_add_f32_e32 v150, v150, v192
	global_atomic_add_f32 v146, v150, s[70:71] offset:640
	s_mov_b64 exec, s[12:13]
	s_waitcnt vmcnt(19)
	v_pk_add_f32 v[16:17], v[16:17], v[186:187]
	v_pk_add_f32 v[14:15], v[14:15], v[184:185]
	v_pk_add_f32 v[12:13], v[12:13], v[190:191]
	v_pk_add_f32 v[10:11], v[10:11], v[188:189]
	v_pk_add_f32 v[8:9], v[8:9], v[198:199]
	v_pk_add_f32 v[6:7], v[6:7], v[196:197]
	v_pk_add_f32 v[4:5], v[4:5], v[206:207]
	v_pk_add_f32 v[2:3], v[2:3], v[204:205]
	global_store_dwordx4 v148, v[14:17], s[8:9] offset:0
	global_store_dwordx4 v148, v[10:13], s[8:9] offset:64
	global_store_dwordx4 v148, v[6:9], s[8:9] offset:512
	global_store_dwordx4 v148, v[2:5], s[8:9] offset:576
	v_cvt_pk_bf16_f32 v184, v14, v15
	v_cvt_pk_bf16_f32 v185, v16, v17
	v_cvt_pk_bf16_f32 v188, v10, v11
	v_cvt_pk_bf16_f32 v189, v12, v13
	v_cvt_pk_bf16_f32 v196, v6, v7
	v_cvt_pk_bf16_f32 v197, v8, v9
	v_cvt_pk_bf16_f32 v204, v2, v3
	v_cvt_pk_bf16_f32 v205, v4, v5
	global_store_dwordx2 v147, v[184:185], s[36:37] offset:0
	global_store_dwordx2 v147, v[188:189], s[36:37] offset:32
	global_store_dwordx2 v147, v[196:197], s[36:37] offset:256
	global_store_dwordx2 v147, v[204:205], s[36:37] offset:288
	v_mul_f32_e32 v150, v15, v15
	v_mul_f32_e32 v151, v17, v17
	v_fmac_f32_e32 v150, v14, v14
	v_fmac_f32_e32 v151, v16, v16
	v_add_f32_e32 v150, v150, v151
	v_mul_f32_e32 v152, v11, v11
	v_mul_f32_e32 v153, v13, v13
	v_fmac_f32_e32 v152, v10, v10
	v_fmac_f32_e32 v153, v12, v12
	v_add_f32_e32 v152, v152, v153
	v_add_f32_e32 v150, v150, v152
	v_mul_f32_e32 v152, v7, v7
	v_mul_f32_e32 v153, v9, v9
	v_fmac_f32_e32 v152, v6, v6
	v_fmac_f32_e32 v153, v8, v8
	v_add_f32_e32 v152, v152, v153
	v_add_f32_e32 v150, v150, v152
	v_mul_f32_e32 v152, v3, v3
	v_mul_f32_e32 v153, v5, v5
	v_fmac_f32_e32 v152, v2, v2
	v_fmac_f32_e32 v153, v4, v4
	v_add_f32_e32 v152, v152, v153
	v_add_f32_e32 v150, v150, v152
	ds_bpermute_b32 v192, v1, v150
	s_waitcnt lgkmcnt(0)
	v_add_f32_e32 v150, v150, v192
	ds_bpermute_b32 v192, v142, v150
	s_and_saveexec_b64 s[12:13], s[6:7]
	s_waitcnt lgkmcnt(0)
	v_add_f32_e32 v150, v150, v192
	global_atomic_add_f32 v146, v150, s[70:71] offset:704
	s_mov_b64 exec, s[12:13]
	s_branch .Lres_done
; __device__ __forceinline__ unsigned cvt_pk_bf16(float lo, float hi) { f32x2 v = {lo, hi}; bf16x2_t b = __builtin_convertvector(v, bf16x2_t); return __builtin_bit_cast(unsigned, b); }
; template <int MODE> __device__ __forceinline__ void gemm_epilogue(f32x4 (&acc)[2][2][4][2], const GD& g, const pg8::Unit& u, int wr, int wc, int fr, int fq, LAS unsigned char* lds, const float (&rsv)[2][4]) {
;     ...
;         const float* base = g.f0; float* out = (float*)g.o0; bf16_t* xb = (bf16_t*)g.o1; float* ssq = (float*)g.f1;
;         const int col0 = u.pn * 256 + wc * 32 + 4 * fq; const int rz = (u.z / g.nz2) * g.ro1;
; #pragma unroll
;         for (int ai = 0; ai < 2; ++ai)
; #pragma unroll
;             for (int m = 0; m < 4; ++m) { const size_t off = (size_t)(rz + rt + ai * 128 + m * 16) * DM + col0;
;                 float ss = 0.f;
; #pragma unroll
;                 for (int bj = 0; bj < 2; ++bj)
; #pragma unroll
;                     for (int n = 0; n < 2; ++n) { const f32x4 bs = *(const f32x4*)(base + off + bj * 128 + n * 16); const f32x4 y = bs + acc[ai][bj][m][n]; *(f32x4*)(out + off + bj * 128 + n * 16) = y;
;                         ss += (y[0] * y[0] + y[1] * y[1]) + (y[2] * y[2] + y[3] * y[3]);
;                         u32x2 w; w.x = cvt_pk_bf16(y[0], y[1]); w.y = cvt_pk_bf16(y[2], y[3]); if (xb) *(u32x2*)(xb + off + bj * 128 + n * 16) = w; }
;                 ss += __shfl_xor(ss, 16); ss += __shfl_xor(ss, 32);
;                 if (fq == 0) __hip_atomic_fetch_add(ssq + rz + rt + ai * 128 + m * 16, ss, __ATOMIC_RELAXED, __HIP_MEMORY_SCOPE_AGENT); }
.Lres_noxb:
	global_load_dwordx4 v[168:171], v143, s[2:3] offset:0 nt
	global_load_dwordx4 v[172:175], v143, s[2:3] offset:64 nt
	global_load_dwordx4 v[176:179], v143, s[2:3] offset:512 nt
	global_load_dwordx4 v[180:183], v143, s[2:3] offset:576 nt
	v_add_u32_e32 v143, 0x20000, v143
	global_load_dwordx4 v[184:187], v143, s[2:3] offset:0 nt
	global_load_dwordx4 v[188:191], v143, s[2:3] offset:64 nt
	global_load_dwordx4 v[196:199], v143, s[2:3] offset:512 nt
	global_load_dwordx4 v[204:207], v143, s[2:3] offset:576 nt
	v_add_u32_e32 v143, 0x20000, v143
	global_load_dwordx4 v[220:223], v143, s[2:3] offset:0 nt
	global_load_dwordx4 v[224:227], v143, s[2:3] offset:64 nt
	global_load_dwordx4 v[228:231], v143, s[2:3] offset:512 nt
	global_load_dwordx4 v[232:235], v143, s[2:3] offset:576 nt
	s_waitcnt vmcnt(8)
	v_pk_add_f32 v[128:129], v[128:129], v[170:171]
	v_pk_add_f32 v[126:127], v[126:127], v[168:169]
	v_pk_add_f32 v[124:125], v[124:125], v[174:175]
	v_pk_add_f32 v[122:123], v[122:123], v[172:173]
	v_pk_add_f32 v[120:121], v[120:121], v[178:179]
	v_pk_add_f32 v[118:119], v[118:119], v[176:177]
	v_pk_add_f32 v[116:117], v[116:117], v[182:183]
	v_pk_add_f32 v[114:115], v[114:115], v[180:181]
	global_store_dwordx4 v148, v[126:129], s[8:9] offset:0
	global_store_dwordx4 v148, v[122:125], s[8:9] offset:64
	global_store_dwordx4 v148, v[118:121], s[8:9] offset:512
	global_store_dwordx4 v148, v[114:117], s[8:9] offset:576
	v_mul_f32_e32 v150, v127, v127
	v_mul_f32_e32 v151, v129, v129
	v_fmac_f32_e32 v150, v126, v126
	v_fmac_f32_e32 v151, v128, v128
	v_add_f32_e32 v150, v150, v151
	v_mul_f32_e32 v152, v123, v123
	v_mul_f32_e32 v153, v125, v125
	v_fmac_f32_e32 v152, v122, v122
	v_fmac_f32_e32 v153, v124, v124
	v_add_f32_e32 v152, v152, v153
	v_add_f32_e32 v150, v150, v152
	v_mul_f32_e32 v152, v119, v119
	v_mul_f32_e32 v153, v121, v121
	v_fmac_f32_e32 v152, v118, v118
	v_fmac_f32_e32 v153, v120, v120
	v_add_f32_e32 v152, v152, v153
	v_add_f32_e32 v150, v150, v152
	v_mul_f32_e32 v152, v115, v115
	v_mul_f32_e32 v153, v117, v117
	v_fmac_f32_e32 v152, v114, v114
	v_fmac_f32_e32 v153, v116, v116
	v_add_f32_e32 v152, v152, v153
	v_add_f32_e32 v150, v150, v152
	ds_bpermute_b32 v192, v1, v150
	v_add_u32_e32 v143, 0x20000, v143
	global_load_dwordx4 v[168:171], v143, s[2:3] offset:0 nt
	global_load_dwordx4 v[172:175], v143, s[2:3] offset:64 nt
	global_load_dwordx4 v[176:179], v143, s[2:3] offset:512 nt
	global_load_dwordx4 v[180:183], v143, s[2:3] offset:576 nt
	s_waitcnt lgkmcnt(0)
	v_add_f32_e32 v150, v150, v192
	ds_bpermute_b32 v192, v142, v150
	v_add_u32_e32 v148, 0x20000, v148
	s_and_saveexec_b64 s[12:13], s[6:7]
	s_waitcnt lgkmcnt(0)
	v_add_f32_e32 v150, v150, v192
	global_atomic_add_f32 v146, v150, s[70:71] offset:0
	s_mov_b64 exec, s[12:13]
	s_waitcnt vmcnt(13)
	v_pk_add_f32 v[112:113], v[112:113], v[186:187]
	v_pk_add_f32 v[110:111], v[110:111], v[184:185]
	v_pk_add_f32 v[108:109], v[108:109], v[190:191]
	v_pk_add_f32 v[106:107], v[106:107], v[188:189]
	v_pk_add_f32 v[104:105], v[104:105], v[198:199]
	v_pk_add_f32 v[102:103], v[102:103], v[196:197]
	v_pk_add_f32 v[100:101], v[100:101], v[206:207]
	v_pk_add_f32 v[98:99], v[98:99], v[204:205]
	global_store_dwordx4 v148, v[110:113], s[8:9] offset:0
	global_store_dwordx4 v148, v[106:109], s[8:9] offset:64
	global_store_dwordx4 v148, v[102:105], s[8:9] offset:512
	global_store_dwordx4 v148, v[98:101], s[8:9] offset:576
	v_mul_f32_e32 v150, v111, v111
	v_mul_f32_e32 v151, v113, v113
	v_fmac_f32_e32 v150, v110, v110
	v_fmac_f32_e32 v151, v112, v112
	v_add_f32_e32 v150, v150, v151
	v_mul_f32_e32 v152, v107, v107
	v_mul_f32_e32 v153, v109, v109
	v_fmac_f32_e32 v152, v106, v106
	v_fmac_f32_e32 v153, v108, v108
	v_add_f32_e32 v152, v152, v153
	v_add_f32_e32 v150, v150, v152
	v_mul_f32_e32 v152, v103, v103
	v_mul_f32_e32 v153, v105, v105
	v_fmac_f32_e32 v152, v102, v102
	v_fmac_f32_e32 v153, v104, v104
	v_add_f32_e32 v152, v152, v153
	v_add_f32_e32 v150, v150, v152
	v_mul_f32_e32 v152, v99, v99
	v_mul_f32_e32 v153, v101, v101
	v_fmac_f32_e32 v152, v98, v98
	v_fmac_f32_e32 v153, v100, v100
	v_add_f32_e32 v152, v152, v153
	v_add_f32_e32 v150, v150, v152
	ds_bpermute_b32 v192, v1, v150
	v_add_u32_e32 v143, 0xa0000, v143
	global_load_dwordx4 v[184:187], v143, s[2:3] offset:0 nt
	global_load_dwordx4 v[188:191], v143, s[2:3] offset:64 nt
	global_load_dwordx4 v[196:199], v143, s[2:3] offset:512 nt
	global_load_dwordx4 v[204:207], v143, s[2:3] offset:576 nt
	s_waitcnt lgkmcnt(0)
	v_add_f32_e32 v150, v150, v192
	ds_bpermute_b32 v192, v142, v150
	v_add_u32_e32 v148, 0x20000, v148
	s_and_saveexec_b64 s[12:13], s[6:7]
	s_waitcnt lgkmcnt(0)
	v_add_f32_e32 v150, v150, v192
	global_atomic_add_f32 v146, v150, s[70:71] offset:64
	s_mov_b64 exec, s[12:13]
	s_waitcnt vmcnt(18)
	v_pk_add_f32 v[96:97], v[96:97], v[222:223]
	v_pk_add_f32 v[94:95], v[94:95], v[220:221]
	v_pk_add_f32 v[92:93], v[92:93], v[226:227]
	v_pk_add_f32 v[90:91], v[90:91], v[224:225]
	v_pk_add_f32 v[88:89], v[88:89], v[230:231]
	v_pk_add_f32 v[86:87], v[86:87], v[228:229]
	v_pk_add_f32 v[84:85], v[84:85], v[234:235]
	v_pk_add_f32 v[82:83], v[82:83], v[232:233]
	global_store_dwordx4 v148, v[94:97], s[8:9] offset:0
	global_store_dwordx4 v148, v[90:93], s[8:9] offset:64
	global_store_dwordx4 v148, v[86:89], s[8:9] offset:512
	global_store_dwordx4 v148, v[82:85], s[8:9] offset:576
	v_mul_f32_e32 v150, v95, v95
	v_mul_f32_e32 v151, v97, v97
	v_fmac_f32_e32 v150, v94, v94
	v_fmac_f32_e32 v151, v96, v96
	v_add_f32_e32 v150, v150, v151
	v_mul_f32_e32 v152, v91, v91
	v_mul_f32_e32 v153, v93, v93
	v_fmac_f32_e32 v152, v90, v90
	v_fmac_f32_e32 v153, v92, v92
	v_add_f32_e32 v152, v152, v153
	v_add_f32_e32 v150, v150, v152
	v_mul_f32_e32 v152, v87, v87
	v_mul_f32_e32 v153, v89, v89
	v_fmac_f32_e32 v152, v86, v86
	v_fmac_f32_e32 v153, v88, v88
	v_add_f32_e32 v152, v152, v153
	v_add_f32_e32 v150, v150, v152
	v_mul_f32_e32 v152, v83, v83
	v_mul_f32_e32 v153, v85, v85
	v_fmac_f32_e32 v152, v82, v82
	v_fmac_f32_e32 v153, v84, v84
	v_add_f32_e32 v152, v152, v153
	v_add_f32_e32 v150, v150, v152
	ds_bpermute_b32 v192, v1, v150
	v_add_u32_e32 v143, 0x20000, v143
	global_load_dwordx4 v[220:223], v143, s[2:3] offset:0 nt
	global_load_dwordx4 v[224:227], v143, s[2:3] offset:64 nt
	global_load_dwordx4 v[228:231], v143, s[2:3] offset:512 nt
	global_load_dwordx4 v[232:235], v143, s[2:3] offset:576 nt
	s_waitcnt lgkmcnt(0)
; __device__ __forceinline__ unsigned cvt_pk_bf16(float lo, float hi) { f32x2 v = {lo, hi}; bf16x2_t b = __builtin_convertvector(v, bf16x2_t); return __builtin_bit_cast(unsigned, b); }
; template <int MODE> __device__ __forceinline__ void gemm_epilogue(f32x4 (&acc)[2][2][4][2], const GD& g, const pg8::Unit& u, int wr, int wc, int fr, int fq, LAS unsigned char* lds, const float (&rsv)[2][4]) {
;     ...
;         const float* base = g.f0; float* out = (float*)g.o0; bf16_t* xb = (bf16_t*)g.o1; float* ssq = (float*)g.f1;
;         const int col0 = u.pn * 256 + wc * 32 + 4 * fq; const int rz = (u.z / g.nz2) * g.ro1;
; #pragma unroll
;         for (int ai = 0; ai < 2; ++ai)
; #pragma unroll
;             for (int m = 0; m < 4; ++m) { const size_t off = (size_t)(rz + rt + ai * 128 + m * 16) * DM + col0;
;                 float ss = 0.f;
; #pragma unroll
;                 for (int bj = 0; bj < 2; ++bj)
; #pragma unroll
;                     for (int n = 0; n < 2; ++n) { const f32x4 bs = *(const f32x4*)(base + off + bj * 128 + n * 16); const f32x4 y = bs + acc[ai][bj][m][n]; *(f32x4*)(out + off + bj * 128 + n * 16) = y;
;                         ss += (y[0] * y[0] + y[1] * y[1]) + (y[2] * y[2] + y[3] * y[3]);
;                         u32x2 w; w.x = cvt_pk_bf16(y[0], y[1]); w.y = cvt_pk_bf16(y[2], y[3]); if (xb) *(u32x2*)(xb + off + bj * 128 + n * 16) = w; }
;                 ss += __shfl_xor(ss, 16); ss += __shfl_xor(ss, 32);
;                 if (fq == 0) __hip_atomic_fetch_add(ssq + rz + rt + ai * 128 + m * 16, ss, __ATOMIC_RELAXED, __HIP_MEMORY_SCOPE_AGENT); }
	v_add_f32_e32 v150, v150, v192
	ds_bpermute_b32 v192, v142, v150
	v_add_u32_e32 v148, 0x20000, v148
	s_and_saveexec_b64 s[12:13], s[6:7]
	s_waitcnt lgkmcnt(0)
	v_add_f32_e32 v150, v150, v192
	global_atomic_add_f32 v146, v150, s[70:71] offset:128
	s_mov_b64 exec, s[12:13]
	s_waitcnt vmcnt(19)
	v_pk_add_f32 v[80:81], v[80:81], v[170:171]
	v_pk_add_f32 v[78:79], v[78:79], v[168:169]
	v_pk_add_f32 v[76:77], v[76:77], v[174:175]
	v_pk_add_f32 v[74:75], v[74:75], v[172:173]
	v_pk_add_f32 v[72:73], v[72:73], v[178:179]
	v_pk_add_f32 v[70:71], v[70:71], v[176:177]
	v_pk_add_f32 v[68:69], v[68:69], v[182:183]
	v_pk_add_f32 v[66:67], v[66:67], v[180:181]
	global_store_dwordx4 v148, v[78:81], s[8:9] offset:0
	global_store_dwordx4 v148, v[74:77], s[8:9] offset:64
	global_store_dwordx4 v148, v[70:73], s[8:9] offset:512
	global_store_dwordx4 v148, v[66:69], s[8:9] offset:576
	v_mul_f32_e32 v150, v79, v79
	v_mul_f32_e32 v151, v81, v81
	v_fmac_f32_e32 v150, v78, v78
	v_fmac_f32_e32 v151, v80, v80
	v_add_f32_e32 v150, v150, v151
	v_mul_f32_e32 v152, v75, v75
	v_mul_f32_e32 v153, v77, v77
	v_fmac_f32_e32 v152, v74, v74
	v_fmac_f32_e32 v153, v76, v76
	v_add_f32_e32 v152, v152, v153
	v_add_f32_e32 v150, v150, v152
	v_mul_f32_e32 v152, v71, v71
	v_mul_f32_e32 v153, v73, v73
	v_fmac_f32_e32 v152, v70, v70
	v_fmac_f32_e32 v153, v72, v72
	v_add_f32_e32 v152, v152, v153
	v_add_f32_e32 v150, v150, v152
	v_mul_f32_e32 v152, v67, v67
	v_mul_f32_e32 v153, v69, v69
	v_fmac_f32_e32 v152, v66, v66
	v_fmac_f32_e32 v153, v68, v68
	v_add_f32_e32 v152, v152, v153
	v_add_f32_e32 v150, v150, v152
	ds_bpermute_b32 v192, v1, v150
	v_add_u32_e32 v143, 0x20000, v143
	global_load_dwordx4 v[168:171], v143, s[2:3] offset:0 nt
	global_load_dwordx4 v[172:175], v143, s[2:3] offset:64 nt
	global_load_dwordx4 v[176:179], v143, s[2:3] offset:512 nt
	global_load_dwordx4 v[180:183], v143, s[2:3] offset:576 nt
	s_waitcnt lgkmcnt(0)
	v_add_f32_e32 v150, v150, v192
	ds_bpermute_b32 v192, v142, v150
	v_add_u32_e32 v148, 0xa0000, v148
	s_and_saveexec_b64 s[12:13], s[6:7]
	s_waitcnt lgkmcnt(0)
	v_add_f32_e32 v150, v150, v192
	global_atomic_add_f32 v146, v150, s[70:71] offset:192
	s_mov_b64 exec, s[12:13]
	s_waitcnt vmcnt(19)
	v_pk_add_f32 v[64:65], v[64:65], v[186:187]
	v_pk_add_f32 v[62:63], v[62:63], v[184:185]
	v_pk_add_f32 v[60:61], v[60:61], v[190:191]
	v_pk_add_f32 v[58:59], v[58:59], v[188:189]
	v_pk_add_f32 v[56:57], v[56:57], v[198:199]
	v_pk_add_f32 v[54:55], v[54:55], v[196:197]
	v_pk_add_f32 v[52:53], v[52:53], v[206:207]
	v_pk_add_f32 v[50:51], v[50:51], v[204:205]
	global_store_dwordx4 v148, v[62:65], s[8:9] offset:0
	global_store_dwordx4 v148, v[58:61], s[8:9] offset:64
	global_store_dwordx4 v148, v[54:57], s[8:9] offset:512
	global_store_dwordx4 v148, v[50:53], s[8:9] offset:576
	v_mul_f32_e32 v150, v63, v63
	v_mul_f32_e32 v151, v65, v65
	v_fmac_f32_e32 v150, v62, v62
	v_fmac_f32_e32 v151, v64, v64
	v_add_f32_e32 v150, v150, v151
	v_mul_f32_e32 v152, v59, v59
	v_mul_f32_e32 v153, v61, v61
	v_fmac_f32_e32 v152, v58, v58
	v_fmac_f32_e32 v153, v60, v60
	v_add_f32_e32 v152, v152, v153
	v_add_f32_e32 v150, v150, v152
	v_mul_f32_e32 v152, v55, v55
	v_mul_f32_e32 v153, v57, v57
	v_fmac_f32_e32 v152, v54, v54
	v_fmac_f32_e32 v153, v56, v56
	v_add_f32_e32 v152, v152, v153
	v_add_f32_e32 v150, v150, v152
	v_mul_f32_e32 v152, v51, v51
	v_mul_f32_e32 v153, v53, v53
	v_fmac_f32_e32 v152, v50, v50
	v_fmac_f32_e32 v153, v52, v52
	v_add_f32_e32 v152, v152, v153
	v_add_f32_e32 v150, v150, v152
	ds_bpermute_b32 v192, v1, v150
	v_add_u32_e32 v143, 0x20000, v143
	global_load_dwordx4 v[184:187], v143, s[2:3] offset:0 nt
	global_load_dwordx4 v[188:191], v143, s[2:3] offset:64 nt
	global_load_dwordx4 v[196:199], v143, s[2:3] offset:512 nt
	global_load_dwordx4 v[204:207], v143, s[2:3] offset:576 nt
	s_waitcnt lgkmcnt(0)
	v_add_f32_e32 v150, v150, v192
	ds_bpermute_b32 v192, v142, v150
	v_add_u32_e32 v148, 0x20000, v148
	s_and_saveexec_b64 s[12:13], s[6:7]
	s_waitcnt lgkmcnt(0)
	v_add_f32_e32 v150, v150, v192
	global_atomic_add_f32 v146, v150, s[70:71] offset:512
	s_mov_b64 exec, s[12:13]
	s_waitcnt vmcnt(19)
; __device__ __forceinline__ unsigned cvt_pk_bf16(float lo, float hi) { f32x2 v = {lo, hi}; bf16x2_t b = __builtin_convertvector(v, bf16x2_t); return __builtin_bit_cast(unsigned, b); }
; template <int MODE> __device__ __forceinline__ void gemm_epilogue(f32x4 (&acc)[2][2][4][2], const GD& g, const pg8::Unit& u, int wr, int wc, int fr, int fq, LAS unsigned char* lds, const float (&rsv)[2][4]) {
;     ...
;         const float* base = g.f0; float* out = (float*)g.o0; bf16_t* xb = (bf16_t*)g.o1; float* ssq = (float*)g.f1;
;         const int col0 = u.pn * 256 + wc * 32 + 4 * fq; const int rz = (u.z / g.nz2) * g.ro1;
; #pragma unroll
;         for (int ai = 0; ai < 2; ++ai)
; #pragma unroll
;             for (int m = 0; m < 4; ++m) { const size_t off = (size_t)(rz + rt + ai * 128 + m * 16) * DM + col0;
;                 float ss = 0.f;
; #pragma unroll
;                 for (int bj = 0; bj < 2; ++bj)
; #pragma unroll
;                     for (int n = 0; n < 2; ++n) { const f32x4 bs = *(const f32x4*)(base + off + bj * 128 + n * 16); const f32x4 y = bs + acc[ai][bj][m][n]; *(f32x4*)(out + off + bj * 128 + n * 16) = y;
;                         ss += (y[0] * y[0] + y[1] * y[1]) + (y[2] * y[2] + y[3] * y[3]);
;                         u32x2 w; w.x = cvt_pk_bf16(y[0], y[1]); w.y = cvt_pk_bf16(y[2], y[3]); if (xb) *(u32x2*)(xb + off + bj * 128 + n * 16) = w; }
;                 ss += __shfl_xor(ss, 16); ss += __shfl_xor(ss, 32);
;                 if (fq == 0) __hip_atomic_fetch_add(ssq + rz + rt + ai * 128 + m * 16, ss, __ATOMIC_RELAXED, __HIP_MEMORY_SCOPE_AGENT); }
	v_pk_add_f32 v[48:49], v[48:49], v[222:223]
	v_pk_add_f32 v[46:47], v[46:47], v[220:221]
	v_pk_add_f32 v[44:45], v[44:45], v[226:227]
	v_pk_add_f32 v[42:43], v[42:43], v[224:225]
	v_pk_add_f32 v[40:41], v[40:41], v[230:231]
	v_pk_add_f32 v[38:39], v[38:39], v[228:229]
	v_pk_add_f32 v[36:37], v[36:37], v[234:235]
	v_pk_add_f32 v[34:35], v[34:35], v[232:233]
	global_store_dwordx4 v148, v[46:49], s[8:9] offset:0
	global_store_dwordx4 v148, v[42:45], s[8:9] offset:64
	global_store_dwordx4 v148, v[38:41], s[8:9] offset:512
	global_store_dwordx4 v148, v[34:37], s[8:9] offset:576
	v_mul_f32_e32 v150, v47, v47
	v_mul_f32_e32 v151, v49, v49
	v_fmac_f32_e32 v150, v46, v46
	v_fmac_f32_e32 v151, v48, v48
	v_add_f32_e32 v150, v150, v151
	v_mul_f32_e32 v152, v43, v43
	v_mul_f32_e32 v153, v45, v45
	v_fmac_f32_e32 v152, v42, v42
	v_fmac_f32_e32 v153, v44, v44
	v_add_f32_e32 v152, v152, v153
	v_add_f32_e32 v150, v150, v152
	v_mul_f32_e32 v152, v39, v39
	v_mul_f32_e32 v153, v41, v41
	v_fmac_f32_e32 v152, v38, v38
	v_fmac_f32_e32 v153, v40, v40
	v_add_f32_e32 v152, v152, v153
	v_add_f32_e32 v150, v150, v152
	v_mul_f32_e32 v152, v35, v35
	v_mul_f32_e32 v153, v37, v37
	v_fmac_f32_e32 v152, v34, v34
	v_fmac_f32_e32 v153, v36, v36
	v_add_f32_e32 v152, v152, v153
	v_add_f32_e32 v150, v150, v152
	ds_bpermute_b32 v192, v1, v150
	s_waitcnt lgkmcnt(0)
	v_add_f32_e32 v150, v150, v192
	ds_bpermute_b32 v192, v142, v150
	v_add_u32_e32 v148, 0x20000, v148
	s_and_saveexec_b64 s[12:13], s[6:7]
	s_waitcnt lgkmcnt(0)
	v_add_f32_e32 v150, v150, v192
	global_atomic_add_f32 v146, v150, s[70:71] offset:576
	s_mov_b64 exec, s[12:13]
	s_waitcnt vmcnt(15)
	v_pk_add_f32 v[32:33], v[32:33], v[170:171]
	v_pk_add_f32 v[30:31], v[30:31], v[168:169]
	v_pk_add_f32 v[28:29], v[28:29], v[174:175]
	v_pk_add_f32 v[26:27], v[26:27], v[172:173]
	v_pk_add_f32 v[24:25], v[24:25], v[178:179]
	v_pk_add_f32 v[22:23], v[22:23], v[176:177]
	v_pk_add_f32 v[20:21], v[20:21], v[182:183]
	v_pk_add_f32 v[18:19], v[18:19], v[180:181]
	global_store_dwordx4 v148, v[30:33], s[8:9] offset:0
	global_store_dwordx4 v148, v[26:29], s[8:9] offset:64
	global_store_dwordx4 v148, v[22:25], s[8:9] offset:512
	global_store_dwordx4 v148, v[18:21], s[8:9] offset:576
	v_mul_f32_e32 v150, v31, v31
	v_mul_f32_e32 v151, v33, v33
	v_fmac_f32_e32 v150, v30, v30
	v_fmac_f32_e32 v151, v32, v32
	v_add_f32_e32 v150, v150, v151
	v_mul_f32_e32 v152, v27, v27
	v_mul_f32_e32 v153, v29, v29
	v_fmac_f32_e32 v152, v26, v26
	v_fmac_f32_e32 v153, v28, v28
	v_add_f32_e32 v152, v152, v153
	v_add_f32_e32 v150, v150, v152
	v_mul_f32_e32 v152, v23, v23
	v_mul_f32_e32 v153, v25, v25
	v_fmac_f32_e32 v152, v22, v22
	v_fmac_f32_e32 v153, v24, v24
	v_add_f32_e32 v152, v152, v153
	v_add_f32_e32 v150, v150, v152
	v_mul_f32_e32 v152, v19, v19
	v_mul_f32_e32 v153, v21, v21
	v_fmac_f32_e32 v152, v18, v18
	v_fmac_f32_e32 v153, v20, v20
	v_add_f32_e32 v152, v152, v153
	v_add_f32_e32 v150, v150, v152
	ds_bpermute_b32 v192, v1, v150
	s_waitcnt lgkmcnt(0)
	v_add_f32_e32 v150, v150, v192
	ds_bpermute_b32 v192, v142, v150
	v_add_u32_e32 v148, 0x20000, v148
	s_and_saveexec_b64 s[12:13], s[6:7]
	s_waitcnt lgkmcnt(0)
	v_add_f32_e32 v150, v150, v192
	global_atomic_add_f32 v146, v150, s[70:71] offset:640
	s_mov_b64 exec, s[12:13]
	s_waitcnt vmcnt(11)
	v_pk_add_f32 v[16:17], v[16:17], v[186:187]
	v_pk_add_f32 v[14:15], v[14:15], v[184:185]
	v_pk_add_f32 v[12:13], v[12:13], v[190:191]
	v_pk_add_f32 v[10:11], v[10:11], v[188:189]
	v_pk_add_f32 v[8:9], v[8:9], v[198:199]
	v_pk_add_f32 v[6:7], v[6:7], v[196:197]
	v_pk_add_f32 v[4:5], v[4:5], v[206:207]
	v_pk_add_f32 v[2:3], v[2:3], v[204:205]
	global_store_dwordx4 v148, v[14:17], s[8:9] offset:0
	global_store_dwordx4 v148, v[10:13], s[8:9] offset:64
	global_store_dwordx4 v148, v[6:9], s[8:9] offset:512
	global_store_dwordx4 v148, v[2:5], s[8:9] offset:576
	v_mul_f32_e32 v150, v15, v15
	v_mul_f32_e32 v151, v17, v17
	v_fmac_f32_e32 v150, v14, v14
	v_fmac_f32_e32 v151, v16, v16
	v_add_f32_e32 v150, v150, v151
	v_mul_f32_e32 v152, v11, v11
	v_mul_f32_e32 v153, v13, v13
	v_fmac_f32_e32 v152, v10, v10
	v_fmac_f32_e32 v153, v12, v12
	v_add_f32_e32 v152, v152, v153
	v_add_f32_e32 v150, v150, v152
	v_mul_f32_e32 v152, v7, v7
	v_mul_f32_e32 v153, v9, v9
	v_fmac_f32_e32 v152, v6, v6
	v_fmac_f32_e32 v153, v8, v8
	v_add_f32_e32 v152, v152, v153
	v_add_f32_e32 v150, v150, v152
	v_mul_f32_e32 v152, v3, v3
	v_mul_f32_e32 v153, v5, v5
	v_fmac_f32_e32 v152, v2, v2
	v_fmac_f32_e32 v153, v4, v4
	v_add_f32_e32 v152, v152, v153
	v_add_f32_e32 v150, v150, v152
	ds_bpermute_b32 v192, v1, v150
	s_waitcnt lgkmcnt(0)
	v_add_f32_e32 v150, v150, v192
	ds_bpermute_b32 v192, v142, v150
	s_and_saveexec_b64 s[12:13], s[6:7]
	s_waitcnt lgkmcnt(0)
	v_add_f32_e32 v150, v150, v192
	global_atomic_add_f32 v146, v150, s[70:71] offset:704
	s_mov_b64 exec, s[12:13]

; __device__ __forceinline__ void final_rows(float* X, const float* gvec, const float* ssq, int nrows, int gw, int ngw, int lane) {
;     for (int row = gw; row < nrows; row += ngw) { const float r = rsqrtf(ssq[row] * (1.f / DM) + EPS);
;         f32x4* xr = (f32x4*)(X + (size_t)row * DM) + lane;
; #pragma unroll
;         for (int j = 0; j < 8; ++j) xr[64 * j] = xr[64 * j] * r * ((const f32x4*)gvec)[lane + 64 * j]; }
; }
.LBB0_644:
	global_load_dword v1, v0, s[6:7]
	global_load_dwordx4 v[24:27], v[12:13], off offset:-4096 nt
	global_load_dwordx4 v[28:31], v[12:13], off offset:-3072 nt
	global_load_dwordx4 v[32:35], v[12:13], off offset:-2048 nt
	global_load_dwordx4 v[36:39], v[12:13], off offset:-1024 nt
	global_load_dwordx4 v[40:43], v[12:13], off nt
	global_load_dwordx4 v[44:47], v[12:13], off offset:1024 nt
	global_load_dwordx4 v[48:51], v[12:13], off offset:2048 nt
	global_load_dwordx4 v[52:55], v[12:13], off offset:3072 nt
	s_add_u32 s6, s6, s2
	s_addc_u32 s7, s7, s3
	s_waitcnt vmcnt(8)
	v_fmamk_f32 v1, v1, 0x3a000000, v203
	v_cmp_gt_f32_e32 vcc, s80, v1
	v_mul_f32_e32 v14, 0x4b800000, v1
	s_nop 0
	v_cndmask_b32_e32 v1, v1, v14, vcc
	v_rsq_f32_e32 v1, v1
	s_nop 0
	v_mul_f32_e32 v14, 0x45800000, v1
	v_cndmask_b32_e32 v14, v1, v14, vcc
	s_waitcnt vmcnt(7)
	v_pk_mul_f32 v[24:25], v[24:25], v[14:15] op_sel_hi:[1,0]
	v_pk_mul_f32 v[26:27], v[26:27], v[14:15] op_sel_hi:[1,0]
	v_pk_mul_f32 v[24:25], v[24:25], v[56:57]
	v_pk_mul_f32 v[26:27], v[26:27], v[58:59]
	global_store_dwordx4 v[12:13], v[24:27], off offset:-4096
	s_waitcnt vmcnt(7)
	v_pk_mul_f32 v[28:29], v[28:29], v[14:15] op_sel_hi:[1,0]
	v_pk_mul_f32 v[30:31], v[30:31], v[14:15] op_sel_hi:[1,0]
	v_pk_mul_f32 v[28:29], v[28:29], v[60:61]
	v_pk_mul_f32 v[30:31], v[30:31], v[62:63]
	global_store_dwordx4 v[12:13], v[28:31], off offset:-3072
	s_waitcnt vmcnt(7)
	v_pk_mul_f32 v[32:33], v[32:33], v[14:15] op_sel_hi:[1,0]
	v_pk_mul_f32 v[34:35], v[34:35], v[14:15] op_sel_hi:[1,0]
	v_pk_mul_f32 v[32:33], v[32:33], v[64:65]
	v_pk_mul_f32 v[34:35], v[34:35], v[66:67]
	global_store_dwordx4 v[12:13], v[32:35], off offset:-2048
	s_waitcnt vmcnt(7)
	v_pk_mul_f32 v[36:37], v[36:37], v[14:15] op_sel_hi:[1,0]
	v_pk_mul_f32 v[38:39], v[38:39], v[14:15] op_sel_hi:[1,0]
	v_pk_mul_f32 v[36:37], v[36:37], v[68:69]
	v_pk_mul_f32 v[38:39], v[38:39], v[70:71]
	global_store_dwordx4 v[12:13], v[36:39], off offset:-1024
	s_waitcnt vmcnt(7)
	v_pk_mul_f32 v[40:41], v[40:41], v[14:15] op_sel_hi:[1,0]
	v_pk_mul_f32 v[42:43], v[42:43], v[14:15] op_sel_hi:[1,0]
	v_pk_mul_f32 v[40:41], v[40:41], v[72:73]
	v_pk_mul_f32 v[42:43], v[42:43], v[74:75]
	global_store_dwordx4 v[12:13], v[40:43], off
	s_waitcnt vmcnt(7)
	v_pk_mul_f32 v[44:45], v[44:45], v[14:15] op_sel_hi:[1,0]
	v_pk_mul_f32 v[46:47], v[46:47], v[14:15] op_sel_hi:[1,0]
	v_pk_mul_f32 v[44:45], v[44:45], v[76:77]
	v_pk_mul_f32 v[46:47], v[46:47], v[78:79]
	global_store_dwordx4 v[12:13], v[44:47], off offset:1024
	s_waitcnt vmcnt(7)
	v_pk_mul_f32 v[48:49], v[48:49], v[14:15] op_sel_hi:[1,0]
	v_pk_mul_f32 v[50:51], v[50:51], v[14:15] op_sel_hi:[1,0]
	v_pk_mul_f32 v[48:49], v[48:49], v[80:81]
	v_pk_mul_f32 v[50:51], v[50:51], v[82:83]
	global_store_dwordx4 v[12:13], v[48:51], off offset:2048
	s_waitcnt vmcnt(7)
	v_pk_mul_f32 v[52:53], v[52:53], v[14:15] op_sel_hi:[1,0]
	v_pk_mul_f32 v[54:55], v[54:55], v[14:15] op_sel_hi:[1,0]
	v_pk_mul_f32 v[52:53], v[52:53], v[84:85]
	v_pk_mul_f32 v[54:55], v[54:55], v[86:87]
	global_store_dwordx4 v[12:13], v[52:55], off offset:3072
	v_lshl_add_u64 v[12:13], v[12:13], 0, s[26:27]
	s_add_i32 s0, s0, s70
	s_cmpk_lt_i32 s0, 0x4000
	s_cbranch_scc1 .LBB0_644

; __device__ __forceinline__ void cvt_tile(const float* W, int ldw, int nvalid, int k0, int n0, bf16_t* WT, int K, int map, int rows_cap, LAS unsigned char* T, int tid, const float* gvec) {
;     const int lane = tid & 63, w = __builtin_amdgcn_readfirstlane(tid >> 6);
;     f32x4 v[2][8];
; #pragma unroll
;     for (int hh = 0; hh < 2; ++hh)
; #pragma unroll
;         for (int rr = 0; rr < 8; ++rr) { const int k = k0 + 8 * w + rr, nc = n0 + 256 * hh + 4 * lane;
;             v[hh][rr] = nc < nvalid ? *(const f32x4*)(W + (size_t)k * ldw + nc) : (f32x4){0.f, 0.f, 0.f, 0.f}; }
.LBB0_870:
	s_ashr_i32 s2, s5, 31
	s_lshr_b32 s2, s2, 30
	s_add_i32 s2, s5, s2
	v_readfirstlane_b32 s9, v194
	s_ashr_i32 s8, s2, 2
	s_ashr_i32 s13, s9, 6
	s_lshl_b32 s2, s8, 6
	s_lshl_b32 s3, s13, 3
	s_add_i32 s10, s3, s2
	s_load_dwordx2 s[2:3], s[24:25], 0x40
	v_add_u32_e32 v2, s0, v1
	s_lshl_b32 s12, s8, 11
	v_subrev_u32_e32 v34, s12, v2
	v_ashrrev_i32_e32 v35, 31, v34
	v_cmp_gt_i32_e32 vcc, s72, v34
	s_waitcnt lgkmcnt(0)
	v_lshl_add_u64 v[68:69], v[34:35], 2, s[2:3]
	v_mov_b32_e32 v6, 0
	v_mov_b32_e32 v2, 0
	v_mov_b32_e32 v3, 0
	v_mov_b32_e32 v4, 0
	v_mov_b32_e32 v5, 0
	s_and_saveexec_b64 s[2:3], vcc
	s_cbranch_execz .LBB0_872
	s_ashr_i32 s11, s10, 31
	s_lshl_b64 s[14:15], s[10:11], 13
	v_lshl_add_u64 v[2:3], v[68:69], 0, s[14:15]
	global_load_dwordx4 v[2:5], v[2:3], off nt
.LBB0_872:
	s_or_b64 exec, exec, s[2:3]
	v_mov_b32_e32 v7, 0
	v_mov_b32_e32 v8, 0
	v_mov_b32_e32 v9, 0
	s_and_saveexec_b64 s[2:3], vcc
	s_cbranch_execz .LBB0_874
	s_or_b32 s14, s10, 1
	s_ashr_i32 s15, s14, 31
	s_lshl_b64 s[14:15], s[14:15], 13
	v_lshl_add_u64 v[6:7], v[68:69], 0, s[14:15]
	global_load_dwordx4 v[6:9], v[6:7], off nt
.LBB0_874:
	s_or_b64 exec, exec, s[2:3]
	v_mov_b32_e32 v10, 0
	v_mov_b32_e32 v14, 0
	v_mov_b32_e32 v15, 0
	v_mov_b32_e32 v16, 0
	v_mov_b32_e32 v17, 0
	s_and_saveexec_b64 s[2:3], vcc
	s_cbranch_execz .LBB0_876
	s_or_b32 s14, s10, 2
	s_ashr_i32 s15, s14, 31
	s_lshl_b64 s[14:15], s[14:15], 13
	v_lshl_add_u64 v[12:13], v[68:69], 0, s[14:15]
	global_load_dwordx4 v[14:17], v[12:13], off nt
.LBB0_876:
	s_or_b64 exec, exec, s[2:3]
	v_mov_b32_e32 v11, 0
	v_mov_b32_e32 v12, 0
	v_mov_b32_e32 v13, 0
	s_and_saveexec_b64 s[2:3], vcc
	s_cbranch_execz .LBB0_878
	s_or_b32 s14, s10, 3
	s_ashr_i32 s15, s14, 31
	s_lshl_b64 s[14:15], s[14:15], 13
	v_lshl_add_u64 v[10:11], v[68:69], 0, s[14:15]
	global_load_dwordx4 v[10:13], v[10:11], off nt
.LBB0_878:
	s_or_b64 exec, exec, s[2:3]
	v_mov_b32_e32 v18, 0
	v_mov_b32_e32 v22, 0
	v_mov_b32_e32 v23, 0
	v_mov_b32_e32 v24, 0
	v_mov_b32_e32 v25, 0
	s_and_saveexec_b64 s[2:3], vcc
	s_cbranch_execz .LBB0_880
	s_or_b32 s14, s10, 4
	s_ashr_i32 s15, s14, 31
	s_lshl_b64 s[14:15], s[14:15], 13
	v_lshl_add_u64 v[20:21], v[68:69], 0, s[14:15]
	global_load_dwordx4 v[22:25], v[20:21], off nt
.LBB0_880:
	s_or_b64 exec, exec, s[2:3]
	v_mov_b32_e32 v19, 0
	v_mov_b32_e32 v20, 0
	v_mov_b32_e32 v21, 0
	s_and_saveexec_b64 s[2:3], vcc
	s_cbranch_execz .LBB0_882
	s_or_b32 s14, s10, 5
	s_ashr_i32 s15, s14, 31
	s_lshl_b64 s[14:15], s[14:15], 13
	v_lshl_add_u64 v[18:19], v[68:69], 0, s[14:15]
	global_load_dwordx4 v[18:21], v[18:19], off nt
.LBB0_882:
	s_or_b64 exec, exec, s[2:3]
	v_mov_b32_e32 v26, 0
	v_mov_b32_e32 v30, 0
	v_mov_b32_e32 v31, 0
	v_mov_b32_e32 v32, 0
	v_mov_b32_e32 v33, 0
	s_and_saveexec_b64 s[2:3], vcc
	s_cbranch_execz .LBB0_884
	s_or_b32 s14, s10, 6
	s_ashr_i32 s15, s14, 31
	s_lshl_b64 s[14:15], s[14:15], 13
	v_lshl_add_u64 v[28:29], v[68:69], 0, s[14:15]
	global_load_dwordx4 v[30:33], v[28:29], off nt
.LBB0_884:
	s_or_b64 exec, exec, s[2:3]
	v_mov_b32_e32 v27, 0
	v_mov_b32_e32 v28, 0
	v_mov_b32_e32 v29, 0
	s_and_saveexec_b64 s[2:3], vcc
	s_cbranch_execz .LBB0_886
	s_or_b32 s14, s10, 7
	s_ashr_i32 s15, s14, 31
	s_lshl_b64 s[14:15], s[14:15], 13
	v_lshl_add_u64 v[26:27], v[68:69], 0, s[14:15]
	global_load_dwordx4 v[26:29], v[26:27], off nt
.LBB0_886:
	s_or_b64 exec, exec, s[2:3]
	v_add_u32_e32 v34, 0x100, v34
	v_cmp_gt_i32_e32 vcc, s72, v34
	v_mov_b32_e32 v38, 0
	v_mov_b32_e32 v34, 0
	v_mov_b32_e32 v35, 0
	v_mov_b32_e32 v36, 0
	v_mov_b32_e32 v37, 0
	s_and_saveexec_b64 s[2:3], vcc
	s_cbranch_execz .LBB0_888
	s_ashr_i32 s11, s10, 31
	s_lshl_b64 s[14:15], s[10:11], 13
	v_lshl_add_u64 v[34:35], v[68:69], 0, s[14:15]
	global_load_dwordx4 v[34:37], v[34:35], off offset:1024 nt
.LBB0_888:
	s_or_b64 exec, exec, s[2:3]
	v_mov_b32_e32 v39, 0
	v_mov_b32_e32 v40, 0
	v_mov_b32_e32 v41, 0
	s_and_saveexec_b64 s[2:3], vcc
	s_cbranch_execz .LBB0_890
	s_or_b32 s14, s10, 1
	s_ashr_i32 s15, s14, 31
	s_lshl_b64 s[14:15], s[14:15], 13
	v_lshl_add_u64 v[38:39], v[68:69], 0, s[14:15]
	global_load_dwordx4 v[38:41], v[38:39], off offset:1024 nt
.LBB0_890:
	s_or_b64 exec, exec, s[2:3]
	v_mov_b32_e32 v42, 0
	v_mov_b32_e32 v46, 0
	v_mov_b32_e32 v47, 0
	v_mov_b32_e32 v48, 0
	v_mov_b32_e32 v49, 0
	s_and_saveexec_b64 s[2:3], vcc
	s_cbranch_execz .LBB0_892
	s_or_b32 s14, s10, 2
	s_ashr_i32 s15, s14, 31
	s_lshl_b64 s[14:15], s[14:15], 13
	v_lshl_add_u64 v[44:45], v[68:69], 0, s[14:15]
	global_load_dwordx4 v[46:49], v[44:45], off offset:1024 nt
.LBB0_892:
	s_or_b64 exec, exec, s[2:3]
	v_mov_b32_e32 v43, 0
	v_mov_b32_e32 v44, 0
	v_mov_b32_e32 v45, 0
	s_and_saveexec_b64 s[2:3], vcc
	s_cbranch_execz .LBB0_894
	s_or_b32 s14, s10, 3
	s_ashr_i32 s15, s14, 31
	s_lshl_b64 s[14:15], s[14:15], 13
	v_lshl_add_u64 v[42:43], v[68:69], 0, s[14:15]
	global_load_dwordx4 v[42:45], v[42:43], off offset:1024 nt
.LBB0_894:
	s_or_b64 exec, exec, s[2:3]
	v_mov_b32_e32 v50, 0
	v_mov_b32_e32 v54, 0
	v_mov_b32_e32 v55, 0
	v_mov_b32_e32 v56, 0
	v_mov_b32_e32 v57, 0
	s_and_saveexec_b64 s[2:3], vcc
	s_cbranch_execz .LBB0_896
	s_or_b32 s14, s10, 4
	s_ashr_i32 s15, s14, 31
	s_lshl_b64 s[14:15], s[14:15], 13
	v_lshl_add_u64 v[52:53], v[68:69], 0, s[14:15]
	global_load_dwordx4 v[54:57], v[52:53], off offset:1024 nt
.LBB0_896:
	s_or_b64 exec, exec, s[2:3]
	v_mov_b32_e32 v51, 0
	v_mov_b32_e32 v52, 0
	v_mov_b32_e32 v53, 0
	s_and_saveexec_b64 s[2:3], vcc
	s_cbranch_execz .LBB0_898
	s_or_b32 s14, s10, 5
	s_ashr_i32 s15, s14, 31
	s_lshl_b64 s[14:15], s[14:15], 13
	v_lshl_add_u64 v[50:51], v[68:69], 0, s[14:15]
	global_load_dwordx4 v[50:53], v[50:51], off offset:1024 nt
.LBB0_898:
	s_or_b64 exec, exec, s[2:3]
	v_mov_b32_e32 v58, 0
	v_mov_b32_e32 v62, 0
	v_mov_b32_e32 v63, 0
	v_mov_b32_e32 v64, 0
	v_mov_b32_e32 v65, 0
	s_and_saveexec_b64 s[2:3], vcc
	s_cbranch_execz .LBB0_900
	s_or_b32 s14, s10, 6
	s_ashr_i32 s15, s14, 31
	s_lshl_b64 s[14:15], s[14:15], 13
	v_lshl_add_u64 v[60:61], v[68:69], 0, s[14:15]
	global_load_dwordx4 v[62:65], v[60:61], off offset:1024 nt
.LBB0_900:
	s_or_b64 exec, exec, s[2:3]
	v_mov_b32_e32 v59, 0
	v_mov_b32_e32 v60, 0
	v_mov_b32_e32 v61, 0
	s_and_saveexec_b64 s[2:3], vcc
	s_cbranch_execz .LBB0_902
	s_or_b32 s10, s10, 7
	s_ashr_i32 s11, s10, 31
	s_lshl_b64 s[10:11], s[10:11], 13
	v_lshl_add_u64 v[58:59], v[68:69], 0, s[10:11]
	global_load_dwordx4 v[58:61], v[58:59], off offset:1024 nt

; __device__ __forceinline__ void cvt_tile(const float* W, int ldw, int nvalid, int k0, int n0, bf16_t* WT, int K, int map, int rows_cap, LAS unsigned char* T, int tid, const float* gvec) {
;     const int lane = tid & 63, w = __builtin_amdgcn_readfirstlane(tid >> 6);
;     f32x4 v[2][8];
; #pragma unroll
;     for (int hh = 0; hh < 2; ++hh)
; #pragma unroll
;         for (int rr = 0; rr < 8; ++rr) { const int k = k0 + 8 * w + rr, nc = n0 + 256 * hh + 4 * lane;
;             v[hh][rr] = nc < nvalid ? *(const f32x4*)(W + (size_t)k * ldw + nc) : (f32x4){0.f, 0.f, 0.f, 0.f}; }
.LBB0_923:
	s_mul_hi_i32 s2, s5, 0x4ec4ec4f
	s_lshr_b32 s3, s2, 31
	s_ashr_i32 s2, s2, 2
	s_add_i32 s14, s2, s3
	s_mul_i32 s3, s14, 0xffffe600
	v_readfirstlane_b32 s15, v194
	s_add_i32 s3, s3, s0
	s_ashr_i32 s18, s15, 6
	v_add_u32_e32 v36, s3, v78
	v_mov_b32_e32 v2, v0
	v_mov_b32_e32 v3, v0
	s_lshl_b32 s2, s14, 6
	s_lshl_b32 s3, s18, 3
	v_ashrrev_i32_e32 v37, 31, v36
	v_mov_b32_e32 v1, v0
	v_mov_b64_e32 v[6:7], v[2:3]
	s_add_i32 s2, s3, s2
	v_cmp_gt_i32_e32 vcc, s19, v36
	v_lshl_add_u64 v[70:71], v[36:37], 2, s[10:11]
	v_mov_b64_e32 v[4:5], v[0:1]
	s_and_saveexec_b64 s[16:17], vcc
	s_cbranch_execz .LBB0_925
	v_mad_i64_i32 v[4:5], s[20:21], s2, v217, v[70:71]
	global_load_dwordx4 v[4:7], v[4:5], off nt
.LBB0_925:
	s_or_b64 exec, exec, s[16:17]
	v_mov_b64_e32 v[10:11], v[2:3]
	v_mov_b64_e32 v[8:9], v[0:1]
	s_and_saveexec_b64 s[16:17], vcc
	s_cbranch_execz .LBB0_927
	s_or_b32 s3, s2, 1
	v_mad_i64_i32 v[2:3], s[20:21], s3, v217, v[70:71]
	global_load_dwordx4 v[8:11], v[2:3], off nt
.LBB0_927:
	s_or_b64 exec, exec, s[16:17]
	v_mov_b32_e32 v2, v0
	v_mov_b32_e32 v3, v0
	v_mov_b32_e32 v1, v0
	v_mov_b64_e32 v[14:15], v[2:3]
	v_mov_b64_e32 v[12:13], v[0:1]
	s_and_saveexec_b64 s[16:17], vcc
	s_cbranch_execz .LBB0_929
	s_or_b32 s3, s2, 2
	v_mad_i64_i32 v[12:13], s[20:21], s3, v217, v[70:71]
	global_load_dwordx4 v[12:15], v[12:13], off nt
.LBB0_929:
	s_or_b64 exec, exec, s[16:17]
	v_mov_b64_e32 v[18:19], v[2:3]
	v_mov_b64_e32 v[16:17], v[0:1]
	s_and_saveexec_b64 s[16:17], vcc
	s_cbranch_execz .LBB0_931
	s_or_b32 s3, s2, 3
	v_mad_i64_i32 v[2:3], s[20:21], s3, v217, v[70:71]
	global_load_dwordx4 v[16:19], v[2:3], off nt
.LBB0_931:
	s_or_b64 exec, exec, s[16:17]
	v_mov_b32_e32 v2, v0
	v_mov_b32_e32 v3, v0
	v_mov_b32_e32 v1, v0
	v_mov_b64_e32 v[22:23], v[2:3]
	v_mov_b64_e32 v[20:21], v[0:1]
	s_and_saveexec_b64 s[16:17], vcc
	s_cbranch_execz .LBB0_933
	s_or_b32 s3, s2, 4
	v_mad_i64_i32 v[20:21], s[20:21], s3, v217, v[70:71]
	global_load_dwordx4 v[20:23], v[20:21], off nt
.LBB0_933:
	s_or_b64 exec, exec, s[16:17]
	v_mov_b64_e32 v[30:31], v[2:3]
	v_mov_b64_e32 v[28:29], v[0:1]
	s_and_saveexec_b64 s[16:17], vcc
	s_cbranch_execz .LBB0_935
	s_or_b32 s3, s2, 5
	v_mad_i64_i32 v[2:3], s[20:21], s3, v217, v[70:71]
	global_load_dwordx4 v[28:31], v[2:3], off nt
.LBB0_935:
	s_or_b64 exec, exec, s[16:17]
	v_mov_b32_e32 v2, v0
	v_mov_b32_e32 v3, v0
	v_mov_b32_e32 v1, v0
	v_mov_b64_e32 v[26:27], v[2:3]
	v_mov_b64_e32 v[24:25], v[0:1]
	s_and_saveexec_b64 s[16:17], vcc
	s_cbranch_execz .LBB0_937
	s_or_b32 s3, s2, 6
	v_mad_i64_i32 v[24:25], s[20:21], s3, v217, v[70:71]
	global_load_dwordx4 v[24:27], v[24:25], off nt
.LBB0_937:
	s_or_b64 exec, exec, s[16:17]
	v_mov_b64_e32 v[34:35], v[2:3]
	v_mov_b64_e32 v[32:33], v[0:1]
	s_and_saveexec_b64 s[16:17], vcc
	s_cbranch_execz .LBB0_939
	s_or_b32 s3, s2, 7
	v_mad_i64_i32 v[2:3], s[20:21], s3, v217, v[70:71]
	global_load_dwordx4 v[32:35], v[2:3], off nt
.LBB0_939:
	s_or_b64 exec, exec, s[16:17]
	v_add_u32_e32 v1, 0x100, v36
	v_mov_b32_e32 v2, v0
	v_mov_b32_e32 v3, v0
	v_cmp_gt_i32_e32 vcc, s19, v1
	v_mov_b32_e32 v1, v0
	v_mov_b64_e32 v[38:39], v[2:3]
	v_mov_b64_e32 v[36:37], v[0:1]
	s_and_saveexec_b64 s[16:17], vcc
	s_cbranch_execz .LBB0_941
	v_mad_i64_i32 v[36:37], s[20:21], s2, v217, v[70:71]
	global_load_dwordx4 v[36:39], v[36:37], off offset:1024 nt
.LBB0_941:
	s_or_b64 exec, exec, s[16:17]
	v_mov_b64_e32 v[42:43], v[2:3]
	v_mov_b64_e32 v[40:41], v[0:1]
	s_and_saveexec_b64 s[16:17], vcc
	s_cbranch_execz .LBB0_943
	s_or_b32 s3, s2, 1
	v_mad_i64_i32 v[2:3], s[20:21], s3, v217, v[70:71]
	global_load_dwordx4 v[40:43], v[2:3], off offset:1024 nt
.LBB0_943:
	s_or_b64 exec, exec, s[16:17]
	v_mov_b32_e32 v2, v0
	v_mov_b32_e32 v3, v0
	v_mov_b32_e32 v1, v0
	v_mov_b64_e32 v[46:47], v[2:3]
	v_mov_b64_e32 v[44:45], v[0:1]
	s_and_saveexec_b64 s[16:17], vcc
	s_cbranch_execz .LBB0_945
	s_or_b32 s3, s2, 2
	v_mad_i64_i32 v[44:45], s[20:21], s3, v217, v[70:71]
	global_load_dwordx4 v[44:47], v[44:45], off offset:1024 nt
.LBB0_945:
	s_or_b64 exec, exec, s[16:17]
	v_mov_b64_e32 v[50:51], v[2:3]
	v_mov_b64_e32 v[48:49], v[0:1]
	s_and_saveexec_b64 s[16:17], vcc
	s_cbranch_execz .LBB0_947
	s_or_b32 s3, s2, 3
	v_mad_i64_i32 v[2:3], s[20:21], s3, v217, v[70:71]
	global_load_dwordx4 v[48:51], v[2:3], off offset:1024 nt
.LBB0_947:
	s_or_b64 exec, exec, s[16:17]
	v_mov_b32_e32 v2, v0
	v_mov_b32_e32 v3, v0
	v_mov_b32_e32 v1, v0
	v_mov_b64_e32 v[54:55], v[2:3]
	v_mov_b64_e32 v[52:53], v[0:1]
	s_and_saveexec_b64 s[16:17], vcc
	s_cbranch_execz .LBB0_949
	s_or_b32 s3, s2, 4
	v_mad_i64_i32 v[52:53], s[20:21], s3, v217, v[70:71]
	global_load_dwordx4 v[52:55], v[52:53], off offset:1024 nt
.LBB0_949:
	s_or_b64 exec, exec, s[16:17]
	v_mov_b64_e32 v[62:63], v[2:3]
	v_mov_b64_e32 v[60:61], v[0:1]
	s_and_saveexec_b64 s[16:17], vcc
	s_cbranch_execz .LBB0_951
	s_or_b32 s3, s2, 5
	v_mad_i64_i32 v[2:3], s[20:21], s3, v217, v[70:71]
	global_load_dwordx4 v[60:63], v[2:3], off offset:1024 nt
.LBB0_951:
	s_or_b64 exec, exec, s[16:17]
	v_mov_b32_e32 v2, v0
	v_mov_b32_e32 v3, v0
	v_mov_b32_e32 v1, v0
	v_mov_b64_e32 v[58:59], v[2:3]
	v_mov_b64_e32 v[56:57], v[0:1]
	s_and_saveexec_b64 s[16:17], vcc
	s_cbranch_execz .LBB0_953
	s_or_b32 s3, s2, 6
	v_mad_i64_i32 v[56:57], s[20:21], s3, v217, v[70:71]
	global_load_dwordx4 v[56:59], v[56:57], off offset:1024 nt
.LBB0_953:
	s_or_b64 exec, exec, s[16:17]
	v_mov_b64_e32 v[66:67], v[2:3]
	v_mov_b64_e32 v[64:65], v[0:1]
	s_and_saveexec_b64 s[16:17], vcc
	s_cbranch_execz .LBB0_955
	s_or_b32 s3, s2, 7
	v_mad_i64_i32 v[2:3], s[20:21], s3, v217, v[70:71]
	global_load_dwordx4 v[64:67], v[2:3], off offset:1024 nt

; __device__ __forceinline__ void cvt_tile(const float* W, int ldw, int nvalid, int k0, int n0, bf16_t* WT, int K, int map, int rows_cap, LAS unsigned char* T, int tid, const float* gvec) {
;     const int lane = tid & 63, w = __builtin_amdgcn_readfirstlane(tid >> 6);
;     f32x4 v[2][8];
; #pragma unroll
;     for (int hh = 0; hh < 2; ++hh)
; #pragma unroll
;         for (int rr = 0; rr < 8; ++rr) { const int k = k0 + 8 * w + rr, nc = n0 + 256 * hh + 4 * lane;
;             v[hh][rr] = nc < nvalid ? *(const f32x4*)(W + (size_t)k * ldw + nc) : (f32x4){0.f, 0.f, 0.f, 0.f}; }
.LBB0_976:
	s_ashr_i32 s2, s5, 31
	s_lshr_b32 s2, s2, 30
	s_add_i32 s2, s5, s2
	v_readfirstlane_b32 s9, v194
	s_ashr_i32 s8, s2, 2
	s_ashr_i32 s13, s9, 6
	s_lshl_b32 s2, s8, 6
	s_lshl_b32 s3, s13, 3
	s_add_i32 s10, s3, s2
	s_load_dwordx2 s[2:3], s[24:25], 0x60
	v_add_u32_e32 v1, s0, v78
	s_lshl_b32 s12, s8, 11
	v_subrev_u32_e32 v34, s12, v1
	v_ashrrev_i32_e32 v35, 31, v34
	v_cmp_gt_i32_e32 vcc, s72, v34
	s_waitcnt lgkmcnt(0)
	v_lshl_add_u64 v[66:67], v[34:35], 2, s[2:3]
	v_mov_b32_e32 v6, 0
	v_mov_b32_e32 v2, 0
	v_mov_b32_e32 v3, 0
	v_mov_b32_e32 v4, 0
	v_mov_b32_e32 v5, 0
	s_and_saveexec_b64 s[2:3], vcc
	s_cbranch_execz .LBB0_978
	s_ashr_i32 s11, s10, 31
	s_lshl_b64 s[14:15], s[10:11], 13
	v_lshl_add_u64 v[2:3], v[66:67], 0, s[14:15]
	global_load_dwordx4 v[2:5], v[2:3], off nt
.LBB0_978:
	s_or_b64 exec, exec, s[2:3]
	v_mov_b32_e32 v7, 0
	v_mov_b32_e32 v8, 0
	v_mov_b32_e32 v9, 0
	s_and_saveexec_b64 s[2:3], vcc
	s_cbranch_execz .LBB0_980
	s_or_b32 s14, s10, 1
	s_ashr_i32 s15, s14, 31
	s_lshl_b64 s[14:15], s[14:15], 13
	v_lshl_add_u64 v[6:7], v[66:67], 0, s[14:15]
	global_load_dwordx4 v[6:9], v[6:7], off nt
.LBB0_980:
	s_or_b64 exec, exec, s[2:3]
	v_mov_b32_e32 v10, 0
	v_mov_b32_e32 v14, 0
	v_mov_b32_e32 v15, 0
	v_mov_b32_e32 v16, 0
	v_mov_b32_e32 v17, 0
	s_and_saveexec_b64 s[2:3], vcc
	s_cbranch_execz .LBB0_982
	s_or_b32 s14, s10, 2
	s_ashr_i32 s15, s14, 31
	s_lshl_b64 s[14:15], s[14:15], 13
	v_lshl_add_u64 v[12:13], v[66:67], 0, s[14:15]
	global_load_dwordx4 v[14:17], v[12:13], off nt
.LBB0_982:
	s_or_b64 exec, exec, s[2:3]
	v_mov_b32_e32 v11, 0
	v_mov_b32_e32 v12, 0
	v_mov_b32_e32 v13, 0
	s_and_saveexec_b64 s[2:3], vcc
	s_cbranch_execz .LBB0_984
	s_or_b32 s14, s10, 3
	s_ashr_i32 s15, s14, 31
	s_lshl_b64 s[14:15], s[14:15], 13
	v_lshl_add_u64 v[10:11], v[66:67], 0, s[14:15]
	global_load_dwordx4 v[10:13], v[10:11], off nt
.LBB0_984:
	s_or_b64 exec, exec, s[2:3]
	v_mov_b32_e32 v18, 0
	v_mov_b32_e32 v22, 0
	v_mov_b32_e32 v23, 0
	v_mov_b32_e32 v24, 0
	v_mov_b32_e32 v25, 0
	s_and_saveexec_b64 s[2:3], vcc
	s_cbranch_execz .LBB0_986
	s_or_b32 s14, s10, 4
	s_ashr_i32 s15, s14, 31
	s_lshl_b64 s[14:15], s[14:15], 13
	v_lshl_add_u64 v[20:21], v[66:67], 0, s[14:15]
	global_load_dwordx4 v[22:25], v[20:21], off nt
.LBB0_986:
	s_or_b64 exec, exec, s[2:3]
	v_mov_b32_e32 v19, 0
	v_mov_b32_e32 v20, 0
	v_mov_b32_e32 v21, 0
	s_and_saveexec_b64 s[2:3], vcc
	s_cbranch_execz .LBB0_988
	s_or_b32 s14, s10, 5
	s_ashr_i32 s15, s14, 31
	s_lshl_b64 s[14:15], s[14:15], 13
	v_lshl_add_u64 v[18:19], v[66:67], 0, s[14:15]
	global_load_dwordx4 v[18:21], v[18:19], off nt
.LBB0_988:
	s_or_b64 exec, exec, s[2:3]
	v_mov_b32_e32 v26, 0
	v_mov_b32_e32 v30, 0
	v_mov_b32_e32 v31, 0
	v_mov_b32_e32 v32, 0
	v_mov_b32_e32 v33, 0
	s_and_saveexec_b64 s[2:3], vcc
	s_cbranch_execz .LBB0_990
	s_or_b32 s14, s10, 6
	s_ashr_i32 s15, s14, 31
	s_lshl_b64 s[14:15], s[14:15], 13
	v_lshl_add_u64 v[28:29], v[66:67], 0, s[14:15]
	global_load_dwordx4 v[30:33], v[28:29], off nt
.LBB0_990:
	s_or_b64 exec, exec, s[2:3]
	v_mov_b32_e32 v27, 0
	v_mov_b32_e32 v28, 0
	v_mov_b32_e32 v29, 0
	s_and_saveexec_b64 s[2:3], vcc
	s_cbranch_execz .LBB0_992
	s_or_b32 s14, s10, 7
	s_ashr_i32 s15, s14, 31
	s_lshl_b64 s[14:15], s[14:15], 13
	v_lshl_add_u64 v[26:27], v[66:67], 0, s[14:15]
	global_load_dwordx4 v[26:29], v[26:27], off nt
.LBB0_992:
	s_or_b64 exec, exec, s[2:3]
	v_add_u32_e32 v1, 0x100, v34
	v_cmp_gt_i32_e32 vcc, s72, v1
	v_mov_b32_e32 v38, 0
	v_mov_b32_e32 v34, 0
	v_mov_b32_e32 v35, 0
	v_mov_b32_e32 v36, 0
	v_mov_b32_e32 v37, 0
	s_and_saveexec_b64 s[2:3], vcc
	s_cbranch_execz .LBB0_994
	s_ashr_i32 s11, s10, 31
	s_lshl_b64 s[14:15], s[10:11], 13
	v_lshl_add_u64 v[34:35], v[66:67], 0, s[14:15]
	global_load_dwordx4 v[34:37], v[34:35], off offset:1024 nt
.LBB0_994:
	s_or_b64 exec, exec, s[2:3]
	v_mov_b32_e32 v39, 0
	v_mov_b32_e32 v40, 0
	v_mov_b32_e32 v41, 0
	s_and_saveexec_b64 s[2:3], vcc
	s_cbranch_execz .LBB0_996
	s_or_b32 s14, s10, 1
	s_ashr_i32 s15, s14, 31
	s_lshl_b64 s[14:15], s[14:15], 13
	v_lshl_add_u64 v[38:39], v[66:67], 0, s[14:15]
	global_load_dwordx4 v[38:41], v[38:39], off offset:1024 nt
.LBB0_996:
	s_or_b64 exec, exec, s[2:3]
	v_mov_b32_e32 v42, 0
	v_mov_b32_e32 v46, 0
	v_mov_b32_e32 v47, 0
	v_mov_b32_e32 v48, 0
	v_mov_b32_e32 v49, 0
	s_and_saveexec_b64 s[2:3], vcc
	s_cbranch_execz .LBB0_998
	s_or_b32 s14, s10, 2
	s_ashr_i32 s15, s14, 31
	s_lshl_b64 s[14:15], s[14:15], 13
	v_lshl_add_u64 v[44:45], v[66:67], 0, s[14:15]
	global_load_dwordx4 v[46:49], v[44:45], off offset:1024 nt
.LBB0_998:
	s_or_b64 exec, exec, s[2:3]
	v_mov_b32_e32 v43, 0
	v_mov_b32_e32 v44, 0
	v_mov_b32_e32 v45, 0
	s_and_saveexec_b64 s[2:3], vcc
	s_cbranch_execz .LBB0_1000
	s_or_b32 s14, s10, 3
	s_ashr_i32 s15, s14, 31
	s_lshl_b64 s[14:15], s[14:15], 13
	v_lshl_add_u64 v[42:43], v[66:67], 0, s[14:15]
	global_load_dwordx4 v[42:45], v[42:43], off offset:1024 nt
.LBB0_1000:
	s_or_b64 exec, exec, s[2:3]
	v_mov_b32_e32 v50, 0
	v_mov_b32_e32 v54, 0
	v_mov_b32_e32 v55, 0
	v_mov_b32_e32 v56, 0
	v_mov_b32_e32 v57, 0
	s_and_saveexec_b64 s[2:3], vcc
	s_cbranch_execz .LBB0_1002
	s_or_b32 s14, s10, 4
	s_ashr_i32 s15, s14, 31
	s_lshl_b64 s[14:15], s[14:15], 13
	v_lshl_add_u64 v[52:53], v[66:67], 0, s[14:15]
	global_load_dwordx4 v[54:57], v[52:53], off offset:1024 nt
.LBB0_1002:
	s_or_b64 exec, exec, s[2:3]
	v_mov_b32_e32 v51, 0
	v_mov_b32_e32 v52, 0
	v_mov_b32_e32 v53, 0
	s_and_saveexec_b64 s[2:3], vcc
	s_cbranch_execz .LBB0_1004
	s_or_b32 s14, s10, 5
	s_ashr_i32 s15, s14, 31
	s_lshl_b64 s[14:15], s[14:15], 13
	v_lshl_add_u64 v[50:51], v[66:67], 0, s[14:15]
	global_load_dwordx4 v[50:53], v[50:51], off offset:1024 nt
.LBB0_1004:
	s_or_b64 exec, exec, s[2:3]
	v_mov_b32_e32 v58, 0
	v_mov_b32_e32 v62, 0
	v_mov_b32_e32 v63, 0
	v_mov_b32_e32 v64, 0
	v_mov_b32_e32 v65, 0
	s_and_saveexec_b64 s[2:3], vcc
	s_cbranch_execz .LBB0_1006
	s_or_b32 s14, s10, 6
	s_ashr_i32 s15, s14, 31
	s_lshl_b64 s[14:15], s[14:15], 13
	v_lshl_add_u64 v[60:61], v[66:67], 0, s[14:15]
	global_load_dwordx4 v[62:65], v[60:61], off offset:1024 nt
.LBB0_1006:
	s_or_b64 exec, exec, s[2:3]
	v_mov_b32_e32 v59, 0
	v_mov_b32_e32 v60, 0
	v_mov_b32_e32 v61, 0
	s_and_saveexec_b64 s[2:3], vcc
	s_cbranch_execz .LBB0_1008
	s_or_b32 s10, s10, 7
	s_ashr_i32 s11, s10, 31
	s_lshl_b64 s[10:11], s[10:11], 13
	v_lshl_add_u64 v[58:59], v[66:67], 0, s[10:11]
	global_load_dwordx4 v[58:61], v[58:59], off offset:1024 nt

; __device__ __forceinline__ unsigned cvt_pk_bf16(float lo, float hi) { f32x2 v = {lo, hi}; bf16x2_t b = __builtin_convertvector(v, bf16x2_t); return __builtin_bit_cast(unsigned, b); }
; __device__ __forceinline__ void cvt_straight(const float* W, bf16_t* O, long n, int tid, int b0, const float* gvec) {
;     const long stride = (long)((int)gridDim.x - b0) * 512 * 8;
;     for (long i = ((long)((int)blockIdx.x - b0) * 512 + tid) * 8; i < n; i += stride) { const float gk = gvec[i >> 11]; const f32x4 a = *(const f32x4*)(W + i) * gk, b = *(const f32x4*)(W + i + 4) * gk;
;         u32x4 w; w.x = cvt_pk_bf16(a[0], a[1]); w.y = cvt_pk_bf16(a[2], a[3]); w.z = cvt_pk_bf16(b[0], b[1]); w.w = cvt_pk_bf16(b[2], b[3]); *(u32x4*)(O + i) = w; }
; }
.LBB0_1028:
	v_ashrrev_i64 v[8:9], 11, v[6:7]
	v_lshl_add_u64 v[8:9], v[8:9], 2, s[42:43]
	global_load_dword v16, v[8:9], off
	s_nop 0
	global_load_dwordx4 v[8:11], v[2:3], off nt
	global_load_dwordx4 v[12:15], v[2:3], off offset:-16 nt
	v_lshl_add_u64 v[6:7], v[6:7], 0, s[66:67]
	s_mov_b64 s[46:47], 0x3fffff
	v_cmp_lt_i64_e32 vcc, s[46:47], v[6:7]
	v_lshl_add_u64 v[2:3], v[2:3], 0, s[88:89]
	s_or_b64 s[44:45], vcc, s[44:45]
	s_waitcnt vmcnt(0)
	v_pk_mul_f32 v[18:19], v[10:11], v[16:17] op_sel_hi:[1,0]
	v_pk_mul_f32 v[14:15], v[14:15], v[16:17] op_sel_hi:[1,0]
	v_pk_mul_f32 v[12:13], v[12:13], v[16:17] op_sel_hi:[1,0]
	v_pk_mul_f32 v[10:11], v[8:9], v[16:17] op_sel_hi:[1,0]
	v_cvt_pk_bf16_f32 v8, v12, v13
	v_cvt_pk_bf16_f32 v9, v14, v15
	v_cvt_pk_bf16_f32 v10, v10, v11
	v_cvt_pk_bf16_f32 v11, v18, v19
	global_store_dwordx4 v[4:5], v[8:11], off
	v_lshl_add_u64 v[4:5], v[4:5], 0, s[96:97]
	s_andn2_b64 exec, exec, s[44:45]
	s_cbranch_execnz .LBB0_1028

; __device__ __forceinline__ void cvt_tile(const float* W, int ldw, int nvalid, int k0, int n0, bf16_t* WT, int K, int map, int rows_cap, LAS unsigned char* T, int tid, const float* gvec) {
;     const int lane = tid & 63, w = __builtin_amdgcn_readfirstlane(tid >> 6);
;     f32x4 v[2][8];
; #pragma unroll
;     for (int hh = 0; hh < 2; ++hh)
; #pragma unroll
;         for (int rr = 0; rr < 8; ++rr) { const int k = k0 + 8 * w + rr, nc = n0 + 256 * hh + 4 * lane;
;             v[hh][rr] = nc < nvalid ? *(const f32x4*)(W + (size_t)k * ldw + nc) : (f32x4){0.f, 0.f, 0.f, 0.f}; }
.LBB0_1032:
	s_ashr_i32 s2, s48, 31
	s_lshr_b32 s2, s2, 29
	s_add_i32 s2, s48, s2
	s_ashr_i32 s44, s2, 3
	v_readfirstlane_b32 s45, v194
	v_add_u32_e32 v1, s49, v78
	s_lshl_b32 s51, s44, 12
	s_ashr_i32 s52, s45, 6
	v_subrev_u32_e32 v34, s51, v1
	s_lshl_b32 s2, s44, 6
	s_lshl_b32 s3, s52, 3
	v_ashrrev_i32_e32 v35, 31, v34
	s_add_i32 s46, s3, s2
	v_cmp_gt_i32_e32 vcc, s40, v34
	v_lshl_add_u64 v[66:67], v[34:35], 2, s[28:29]
	v_mov_b32_e32 v6, 0
	v_mov_b32_e32 v2, 0
	v_mov_b32_e32 v3, 0
	v_mov_b32_e32 v4, 0
	v_mov_b32_e32 v5, 0
	s_and_saveexec_b64 s[2:3], vcc
	s_cbranch_execz .LBB0_1034
	s_ashr_i32 s47, s46, 31
	s_lshl_b64 s[56:57], s[46:47], 14
	v_lshl_add_u64 v[2:3], v[66:67], 0, s[56:57]
	global_load_dwordx4 v[2:5], v[2:3], off nt
.LBB0_1034:
	s_or_b64 exec, exec, s[2:3]
	v_mov_b32_e32 v7, 0
	v_mov_b32_e32 v8, 0
	v_mov_b32_e32 v9, 0
	s_and_saveexec_b64 s[2:3], vcc
	s_cbranch_execz .LBB0_1036
	s_or_b32 s56, s46, 1
	s_ashr_i32 s57, s56, 31
	s_lshl_b64 s[56:57], s[56:57], 14
	v_lshl_add_u64 v[6:7], v[66:67], 0, s[56:57]
	global_load_dwordx4 v[6:9], v[6:7], off nt
.LBB0_1036:
	s_or_b64 exec, exec, s[2:3]
	v_mov_b32_e32 v10, 0
	v_mov_b32_e32 v14, 0
	v_mov_b32_e32 v15, 0
	v_mov_b32_e32 v16, 0
	v_mov_b32_e32 v17, 0
	s_and_saveexec_b64 s[2:3], vcc
	s_cbranch_execz .LBB0_1038
	s_or_b32 s56, s46, 2
	s_ashr_i32 s57, s56, 31
	s_lshl_b64 s[56:57], s[56:57], 14
	v_lshl_add_u64 v[12:13], v[66:67], 0, s[56:57]
	global_load_dwordx4 v[14:17], v[12:13], off nt
.LBB0_1038:
	s_or_b64 exec, exec, s[2:3]
	v_mov_b32_e32 v11, 0
	v_mov_b32_e32 v12, 0
	v_mov_b32_e32 v13, 0
	s_and_saveexec_b64 s[2:3], vcc
	s_cbranch_execz .LBB0_1040
	s_or_b32 s56, s46, 3
	s_ashr_i32 s57, s56, 31
	s_lshl_b64 s[56:57], s[56:57], 14
	v_lshl_add_u64 v[10:11], v[66:67], 0, s[56:57]
	global_load_dwordx4 v[10:13], v[10:11], off nt
.LBB0_1040:
	s_or_b64 exec, exec, s[2:3]
	v_mov_b32_e32 v18, 0
	v_mov_b32_e32 v22, 0
	v_mov_b32_e32 v23, 0
	v_mov_b32_e32 v24, 0
	v_mov_b32_e32 v25, 0
	s_and_saveexec_b64 s[2:3], vcc
	s_cbranch_execz .LBB0_1042
	s_or_b32 s56, s46, 4
	s_ashr_i32 s57, s56, 31
	s_lshl_b64 s[56:57], s[56:57], 14
	v_lshl_add_u64 v[20:21], v[66:67], 0, s[56:57]
	global_load_dwordx4 v[22:25], v[20:21], off nt
.LBB0_1042:
	s_or_b64 exec, exec, s[2:3]
	v_mov_b32_e32 v19, 0
	v_mov_b32_e32 v20, 0
	v_mov_b32_e32 v21, 0
	s_and_saveexec_b64 s[2:3], vcc
	s_cbranch_execz .LBB0_1044
	s_or_b32 s56, s46, 5
	s_ashr_i32 s57, s56, 31
	s_lshl_b64 s[56:57], s[56:57], 14
	v_lshl_add_u64 v[18:19], v[66:67], 0, s[56:57]
	global_load_dwordx4 v[18:21], v[18:19], off nt
.LBB0_1044:
	s_or_b64 exec, exec, s[2:3]
	v_mov_b32_e32 v26, 0
	v_mov_b32_e32 v30, 0
	v_mov_b32_e32 v31, 0
	v_mov_b32_e32 v32, 0
	v_mov_b32_e32 v33, 0
	s_and_saveexec_b64 s[2:3], vcc
	s_cbranch_execz .LBB0_1046
	s_or_b32 s56, s46, 6
	s_ashr_i32 s57, s56, 31
	s_lshl_b64 s[56:57], s[56:57], 14
	v_lshl_add_u64 v[28:29], v[66:67], 0, s[56:57]
	global_load_dwordx4 v[30:33], v[28:29], off nt
.LBB0_1046:
	s_or_b64 exec, exec, s[2:3]
	v_mov_b32_e32 v27, 0
	v_mov_b32_e32 v28, 0
	v_mov_b32_e32 v29, 0
	s_and_saveexec_b64 s[2:3], vcc
	s_cbranch_execz .LBB0_1048
	s_or_b32 s56, s46, 7
	s_ashr_i32 s57, s56, 31
	s_lshl_b64 s[56:57], s[56:57], 14
	v_lshl_add_u64 v[26:27], v[66:67], 0, s[56:57]
	global_load_dwordx4 v[26:29], v[26:27], off nt
.LBB0_1048:
	s_or_b64 exec, exec, s[2:3]
	v_add_u32_e32 v1, 0x100, v34
	v_cmp_gt_i32_e32 vcc, s40, v1
	v_mov_b32_e32 v38, 0
	v_mov_b32_e32 v34, 0
	v_mov_b32_e32 v35, 0
	v_mov_b32_e32 v36, 0
	v_mov_b32_e32 v37, 0
	s_and_saveexec_b64 s[2:3], vcc
	s_cbranch_execz .LBB0_1050
	s_ashr_i32 s47, s46, 31
	s_lshl_b64 s[56:57], s[46:47], 14
	v_lshl_add_u64 v[34:35], v[66:67], 0, s[56:57]
	global_load_dwordx4 v[34:37], v[34:35], off offset:1024 nt
.LBB0_1050:
	s_or_b64 exec, exec, s[2:3]
	v_mov_b32_e32 v39, 0
	v_mov_b32_e32 v40, 0
	v_mov_b32_e32 v41, 0
	s_and_saveexec_b64 s[2:3], vcc
	s_cbranch_execz .LBB0_1052
	s_or_b32 s56, s46, 1
	s_ashr_i32 s57, s56, 31
	s_lshl_b64 s[56:57], s[56:57], 14
	v_lshl_add_u64 v[38:39], v[66:67], 0, s[56:57]
	global_load_dwordx4 v[38:41], v[38:39], off offset:1024 nt
.LBB0_1052:
	s_or_b64 exec, exec, s[2:3]
	v_mov_b32_e32 v42, 0
	v_mov_b32_e32 v46, 0
	v_mov_b32_e32 v47, 0
	v_mov_b32_e32 v48, 0
	v_mov_b32_e32 v49, 0
	s_and_saveexec_b64 s[2:3], vcc
	s_cbranch_execz .LBB0_1054
	s_or_b32 s56, s46, 2
	s_ashr_i32 s57, s56, 31
	s_lshl_b64 s[56:57], s[56:57], 14
	v_lshl_add_u64 v[44:45], v[66:67], 0, s[56:57]
	global_load_dwordx4 v[46:49], v[44:45], off offset:1024 nt
.LBB0_1054:
	s_or_b64 exec, exec, s[2:3]
	v_mov_b32_e32 v43, 0
	v_mov_b32_e32 v44, 0
	v_mov_b32_e32 v45, 0
	s_and_saveexec_b64 s[2:3], vcc
	s_cbranch_execz .LBB0_1056
	s_or_b32 s56, s46, 3
	s_ashr_i32 s57, s56, 31
	s_lshl_b64 s[56:57], s[56:57], 14
	v_lshl_add_u64 v[42:43], v[66:67], 0, s[56:57]
	global_load_dwordx4 v[42:45], v[42:43], off offset:1024 nt
.LBB0_1056:
	s_or_b64 exec, exec, s[2:3]
	v_mov_b32_e32 v50, 0
	v_mov_b32_e32 v54, 0
	v_mov_b32_e32 v55, 0
	v_mov_b32_e32 v56, 0
	v_mov_b32_e32 v57, 0
	s_and_saveexec_b64 s[2:3], vcc
	s_cbranch_execz .LBB0_1058
	s_or_b32 s56, s46, 4
	s_ashr_i32 s57, s56, 31
	s_lshl_b64 s[56:57], s[56:57], 14
	v_lshl_add_u64 v[52:53], v[66:67], 0, s[56:57]
	global_load_dwordx4 v[54:57], v[52:53], off offset:1024 nt
.LBB0_1058:
	s_or_b64 exec, exec, s[2:3]
	v_mov_b32_e32 v51, 0
	v_mov_b32_e32 v52, 0
	v_mov_b32_e32 v53, 0
	s_and_saveexec_b64 s[2:3], vcc
	s_cbranch_execz .LBB0_1060
	s_or_b32 s56, s46, 5
	s_ashr_i32 s57, s56, 31
	s_lshl_b64 s[56:57], s[56:57], 14
	v_lshl_add_u64 v[50:51], v[66:67], 0, s[56:57]
	global_load_dwordx4 v[50:53], v[50:51], off offset:1024 nt
.LBB0_1060:
	s_or_b64 exec, exec, s[2:3]
	v_mov_b32_e32 v58, 0
	v_mov_b32_e32 v62, 0
	v_mov_b32_e32 v63, 0
	v_mov_b32_e32 v64, 0
	v_mov_b32_e32 v65, 0
	s_and_saveexec_b64 s[2:3], vcc
	s_cbranch_execz .LBB0_1062
	s_or_b32 s56, s46, 6
	s_ashr_i32 s57, s56, 31
	s_lshl_b64 s[56:57], s[56:57], 14
	v_lshl_add_u64 v[60:61], v[66:67], 0, s[56:57]
	global_load_dwordx4 v[62:65], v[60:61], off offset:1024 nt
.LBB0_1062:
	s_or_b64 exec, exec, s[2:3]
	v_mov_b32_e32 v59, 0
	v_mov_b32_e32 v60, 0
	v_mov_b32_e32 v61, 0
	s_and_saveexec_b64 s[2:3], vcc
	s_cbranch_execz .LBB0_1064
	s_or_b32 s46, s46, 7
	s_ashr_i32 s47, s46, 31
	s_lshl_b64 s[46:47], s[46:47], 14
	v_lshl_add_u64 v[58:59], v[66:67], 0, s[46:47]
	global_load_dwordx4 v[58:61], v[58:59], off offset:1024 nt

; __device__ __forceinline__ void cvt_tile(const float* W, int ldw, int nvalid, int k0, int n0, bf16_t* WT, int K, int map, int rows_cap, LAS unsigned char* T, int tid, const float* gvec) {
;     const int lane = tid & 63, w = __builtin_amdgcn_readfirstlane(tid >> 6);
;     f32x4 v[2][8];
; #pragma unroll
;     for (int hh = 0; hh < 2; ++hh)
; #pragma unroll
;         for (int rr = 0; rr < 8; ++rr) { const int k = k0 + 8 * w + rr, nc = n0 + 256 * hh + 4 * lane;
;             v[hh][rr] = nc < nvalid ? *(const f32x4*)(W + (size_t)k * ldw + nc) : (f32x4){0.f, 0.f, 0.f, 0.f}; }
.LBB0_1083:
	s_ashr_i32 s2, s48, 31
	s_lshr_b32 s2, s2, 30
	s_add_i32 s2, s48, s2
	s_ashr_i32 s44, s2, 2
	v_readfirstlane_b32 s45, v194
	v_add_u32_e32 v1, s49, v78
	s_lshl_b32 s51, s44, 11
	s_ashr_i32 s52, s45, 6
	v_subrev_u32_e32 v34, s51, v1
	s_lshl_b32 s2, s44, 6
	s_lshl_b32 s3, s52, 3
	v_ashrrev_i32_e32 v35, 31, v34
	s_add_i32 s46, s3, s2
	v_cmp_gt_i32_e32 vcc, s72, v34
	v_lshl_add_u64 v[66:67], v[34:35], 2, s[28:29]
	v_mov_b32_e32 v6, 0
	v_mov_b32_e32 v2, 0
	v_mov_b32_e32 v3, 0
	v_mov_b32_e32 v4, 0
	v_mov_b32_e32 v5, 0
	s_and_saveexec_b64 s[2:3], vcc
	s_cbranch_execz .LBB0_1085
	s_ashr_i32 s47, s46, 31
	s_lshl_b64 s[56:57], s[46:47], 13
	v_lshl_add_u64 v[2:3], v[66:67], 0, s[56:57]
	global_load_dwordx4 v[2:5], v[2:3], off nt
.LBB0_1085:
	s_or_b64 exec, exec, s[2:3]
	v_mov_b32_e32 v7, 0
	v_mov_b32_e32 v8, 0
	v_mov_b32_e32 v9, 0
	s_and_saveexec_b64 s[2:3], vcc
	s_cbranch_execz .LBB0_1087
	s_or_b32 s56, s46, 1
	s_ashr_i32 s57, s56, 31
	s_lshl_b64 s[56:57], s[56:57], 13
	v_lshl_add_u64 v[6:7], v[66:67], 0, s[56:57]
	global_load_dwordx4 v[6:9], v[6:7], off nt
.LBB0_1087:
	s_or_b64 exec, exec, s[2:3]
	v_mov_b32_e32 v10, 0
	v_mov_b32_e32 v14, 0
	v_mov_b32_e32 v15, 0
	v_mov_b32_e32 v16, 0
	v_mov_b32_e32 v17, 0
	s_and_saveexec_b64 s[2:3], vcc
	s_cbranch_execz .LBB0_1089
	s_or_b32 s56, s46, 2
	s_ashr_i32 s57, s56, 31
	s_lshl_b64 s[56:57], s[56:57], 13
	v_lshl_add_u64 v[12:13], v[66:67], 0, s[56:57]
	global_load_dwordx4 v[14:17], v[12:13], off nt
.LBB0_1089:
	s_or_b64 exec, exec, s[2:3]
	v_mov_b32_e32 v11, 0
	v_mov_b32_e32 v12, 0
	v_mov_b32_e32 v13, 0
	s_and_saveexec_b64 s[2:3], vcc
	s_cbranch_execz .LBB0_1091
	s_or_b32 s56, s46, 3
	s_ashr_i32 s57, s56, 31
	s_lshl_b64 s[56:57], s[56:57], 13
	v_lshl_add_u64 v[10:11], v[66:67], 0, s[56:57]
	global_load_dwordx4 v[10:13], v[10:11], off nt
.LBB0_1091:
	s_or_b64 exec, exec, s[2:3]
	v_mov_b32_e32 v18, 0
	v_mov_b32_e32 v22, 0
	v_mov_b32_e32 v23, 0
	v_mov_b32_e32 v24, 0
	v_mov_b32_e32 v25, 0
	s_and_saveexec_b64 s[2:3], vcc
	s_cbranch_execz .LBB0_1093
	s_or_b32 s56, s46, 4
	s_ashr_i32 s57, s56, 31
	s_lshl_b64 s[56:57], s[56:57], 13
	v_lshl_add_u64 v[20:21], v[66:67], 0, s[56:57]
	global_load_dwordx4 v[22:25], v[20:21], off nt
.LBB0_1093:
	s_or_b64 exec, exec, s[2:3]
	v_mov_b32_e32 v19, 0
	v_mov_b32_e32 v20, 0
	v_mov_b32_e32 v21, 0
	s_and_saveexec_b64 s[2:3], vcc
	s_cbranch_execz .LBB0_1095
	s_or_b32 s56, s46, 5
	s_ashr_i32 s57, s56, 31
	s_lshl_b64 s[56:57], s[56:57], 13
	v_lshl_add_u64 v[18:19], v[66:67], 0, s[56:57]
	global_load_dwordx4 v[18:21], v[18:19], off nt
.LBB0_1095:
	s_or_b64 exec, exec, s[2:3]
	v_mov_b32_e32 v26, 0
	v_mov_b32_e32 v30, 0
	v_mov_b32_e32 v31, 0
	v_mov_b32_e32 v32, 0
	v_mov_b32_e32 v33, 0
	s_and_saveexec_b64 s[2:3], vcc
	s_cbranch_execz .LBB0_1097
	s_or_b32 s56, s46, 6
	s_ashr_i32 s57, s56, 31
	s_lshl_b64 s[56:57], s[56:57], 13
	v_lshl_add_u64 v[28:29], v[66:67], 0, s[56:57]
	global_load_dwordx4 v[30:33], v[28:29], off nt
.LBB0_1097:
	s_or_b64 exec, exec, s[2:3]
	v_mov_b32_e32 v27, 0
	v_mov_b32_e32 v28, 0
	v_mov_b32_e32 v29, 0
	s_and_saveexec_b64 s[2:3], vcc
	s_cbranch_execz .LBB0_1099
	s_or_b32 s56, s46, 7
	s_ashr_i32 s57, s56, 31
	s_lshl_b64 s[56:57], s[56:57], 13
	v_lshl_add_u64 v[26:27], v[66:67], 0, s[56:57]
	global_load_dwordx4 v[26:29], v[26:27], off nt
.LBB0_1099:
	s_or_b64 exec, exec, s[2:3]
	v_add_u32_e32 v1, 0x100, v34
	v_cmp_gt_i32_e32 vcc, s72, v1
	v_mov_b32_e32 v38, 0
	v_mov_b32_e32 v34, 0
	v_mov_b32_e32 v35, 0
	v_mov_b32_e32 v36, 0
	v_mov_b32_e32 v37, 0
	s_and_saveexec_b64 s[2:3], vcc
	s_cbranch_execz .LBB0_1101
	s_ashr_i32 s47, s46, 31
	s_lshl_b64 s[56:57], s[46:47], 13
	v_lshl_add_u64 v[34:35], v[66:67], 0, s[56:57]
	global_load_dwordx4 v[34:37], v[34:35], off offset:1024 nt
.LBB0_1101:
	s_or_b64 exec, exec, s[2:3]
	v_mov_b32_e32 v39, 0
	v_mov_b32_e32 v40, 0
	v_mov_b32_e32 v41, 0
	s_and_saveexec_b64 s[2:3], vcc
	s_cbranch_execz .LBB0_1103
	s_or_b32 s56, s46, 1
	s_ashr_i32 s57, s56, 31
	s_lshl_b64 s[56:57], s[56:57], 13
	v_lshl_add_u64 v[38:39], v[66:67], 0, s[56:57]
	global_load_dwordx4 v[38:41], v[38:39], off offset:1024 nt
.LBB0_1103:
	s_or_b64 exec, exec, s[2:3]
	v_mov_b32_e32 v42, 0
	v_mov_b32_e32 v46, 0
	v_mov_b32_e32 v47, 0
	v_mov_b32_e32 v48, 0
	v_mov_b32_e32 v49, 0
	s_and_saveexec_b64 s[2:3], vcc
	s_cbranch_execz .LBB0_1105
	s_or_b32 s56, s46, 2
	s_ashr_i32 s57, s56, 31
	s_lshl_b64 s[56:57], s[56:57], 13
	v_lshl_add_u64 v[44:45], v[66:67], 0, s[56:57]
	global_load_dwordx4 v[46:49], v[44:45], off offset:1024 nt
.LBB0_1105:
	s_or_b64 exec, exec, s[2:3]
	v_mov_b32_e32 v43, 0
	v_mov_b32_e32 v44, 0
	v_mov_b32_e32 v45, 0
	s_and_saveexec_b64 s[2:3], vcc
	s_cbranch_execz .LBB0_1107
	s_or_b32 s56, s46, 3
	s_ashr_i32 s57, s56, 31
	s_lshl_b64 s[56:57], s[56:57], 13
	v_lshl_add_u64 v[42:43], v[66:67], 0, s[56:57]
	global_load_dwordx4 v[42:45], v[42:43], off offset:1024 nt
.LBB0_1107:
	s_or_b64 exec, exec, s[2:3]
	v_mov_b32_e32 v50, 0
	v_mov_b32_e32 v54, 0
	v_mov_b32_e32 v55, 0
	v_mov_b32_e32 v56, 0
	v_mov_b32_e32 v57, 0
	s_and_saveexec_b64 s[2:3], vcc
	s_cbranch_execz .LBB0_1109
	s_or_b32 s56, s46, 4
	s_ashr_i32 s57, s56, 31
	s_lshl_b64 s[56:57], s[56:57], 13
	v_lshl_add_u64 v[52:53], v[66:67], 0, s[56:57]
	global_load_dwordx4 v[54:57], v[52:53], off offset:1024 nt
.LBB0_1109:
	s_or_b64 exec, exec, s[2:3]
	v_mov_b32_e32 v51, 0
	v_mov_b32_e32 v52, 0
	v_mov_b32_e32 v53, 0
	s_and_saveexec_b64 s[2:3], vcc
	s_cbranch_execz .LBB0_1111
	s_or_b32 s56, s46, 5
	s_ashr_i32 s57, s56, 31
	s_lshl_b64 s[56:57], s[56:57], 13
	v_lshl_add_u64 v[50:51], v[66:67], 0, s[56:57]
	global_load_dwordx4 v[50:53], v[50:51], off offset:1024 nt
.LBB0_1111:
	s_or_b64 exec, exec, s[2:3]
	v_mov_b32_e32 v58, 0
	v_mov_b32_e32 v62, 0
	v_mov_b32_e32 v63, 0
	v_mov_b32_e32 v64, 0
	v_mov_b32_e32 v65, 0
	s_and_saveexec_b64 s[2:3], vcc
	s_cbranch_execz .LBB0_1113
	s_or_b32 s56, s46, 6
	s_ashr_i32 s57, s56, 31
	s_lshl_b64 s[56:57], s[56:57], 13
	v_lshl_add_u64 v[60:61], v[66:67], 0, s[56:57]
	global_load_dwordx4 v[62:65], v[60:61], off offset:1024 nt
.LBB0_1113:
	s_or_b64 exec, exec, s[2:3]
	v_mov_b32_e32 v59, 0
	v_mov_b32_e32 v60, 0
	v_mov_b32_e32 v61, 0
	s_and_saveexec_b64 s[2:3], vcc
	s_cbranch_execz .LBB0_1115
	s_or_b32 s46, s46, 7
	s_ashr_i32 s47, s46, 31
	s_lshl_b64 s[46:47], s[46:47], 13
	v_lshl_add_u64 v[58:59], v[66:67], 0, s[46:47]
	global_load_dwordx4 v[58:61], v[58:59], off offset:1024 nt

; __device__ __forceinline__ void cvt_tile(const float* W, int ldw, int nvalid, int k0, int n0, bf16_t* WT, int K, int map, int rows_cap, LAS unsigned char* T, int tid, const float* gvec) {
;     const int lane = tid & 63, w = __builtin_amdgcn_readfirstlane(tid >> 6);
;     f32x4 v[2][8];
; #pragma unroll
;     for (int hh = 0; hh < 2; ++hh)
; #pragma unroll
;         for (int rr = 0; rr < 8; ++rr) { const int k = k0 + 8 * w + rr, nc = n0 + 256 * hh + 4 * lane;
;             v[hh][rr] = nc < nvalid ? *(const f32x4*)(W + (size_t)k * ldw + nc) : (f32x4){0.f, 0.f, 0.f, 0.f}; }
.LBB0_1134:
	s_mul_hi_i32 s2, s50, 0x2e8ba2e9
	s_lshr_b32 s3, s2, 31
	s_ashr_i32 s2, s2, 1
	s_add_i32 s44, s2, s3
	s_mul_i32 s3, s44, 0xffffea00
	v_readfirstlane_b32 s45, v194
	s_add_i32 s3, s3, s51
	s_ashr_i32 s53, s45, 6
	v_add_u32_e32 v36, s3, v78
	v_mov_b32_e32 v2, v0
	v_mov_b32_e32 v3, v0
	s_lshl_b32 s2, s44, 6
	s_lshl_b32 s3, s53, 3
	v_ashrrev_i32_e32 v37, 31, v36
	v_mov_b32_e32 v1, v0
	v_mov_b64_e32 v[6:7], v[2:3]
	s_add_i32 s2, s3, s2
	v_cmp_gt_i32_e32 vcc, s54, v36
	v_lshl_add_u64 v[76:77], v[36:37], 2, s[26:27]
	v_mov_b64_e32 v[4:5], v[0:1]
	s_and_saveexec_b64 s[46:47], vcc
	s_cbranch_execz .LBB0_1136
	v_mad_i64_i32 v[4:5], s[56:57], s2, v218, v[76:77]
	global_load_dwordx4 v[4:7], v[4:5], off nt
.LBB0_1136:
	s_or_b64 exec, exec, s[46:47]
	v_mov_b64_e32 v[10:11], v[2:3]
	v_mov_b64_e32 v[8:9], v[0:1]
	s_and_saveexec_b64 s[46:47], vcc
	s_cbranch_execz .LBB0_1138
	s_or_b32 s3, s2, 1
	v_mad_i64_i32 v[2:3], s[56:57], s3, v218, v[76:77]
	global_load_dwordx4 v[8:11], v[2:3], off nt
.LBB0_1138:
	s_or_b64 exec, exec, s[46:47]
	v_mov_b32_e32 v2, v0
	v_mov_b32_e32 v3, v0
	v_mov_b32_e32 v1, v0
	v_mov_b64_e32 v[14:15], v[2:3]
	v_mov_b64_e32 v[12:13], v[0:1]
	s_and_saveexec_b64 s[46:47], vcc
	s_cbranch_execz .LBB0_1140
	s_or_b32 s3, s2, 2
	v_mad_i64_i32 v[12:13], s[56:57], s3, v218, v[76:77]
	global_load_dwordx4 v[12:15], v[12:13], off nt
.LBB0_1140:
	s_or_b64 exec, exec, s[46:47]
	v_mov_b64_e32 v[18:19], v[2:3]
	v_mov_b64_e32 v[16:17], v[0:1]
	s_and_saveexec_b64 s[46:47], vcc
	s_cbranch_execz .LBB0_1142
	s_or_b32 s3, s2, 3
	v_mad_i64_i32 v[2:3], s[56:57], s3, v218, v[76:77]
	global_load_dwordx4 v[16:19], v[2:3], off nt
.LBB0_1142:
	s_or_b64 exec, exec, s[46:47]
	v_mov_b32_e32 v2, v0
	v_mov_b32_e32 v3, v0
	v_mov_b32_e32 v1, v0
	v_mov_b64_e32 v[22:23], v[2:3]
	v_mov_b64_e32 v[20:21], v[0:1]
	s_and_saveexec_b64 s[46:47], vcc
	s_cbranch_execz .LBB0_1144
	s_or_b32 s3, s2, 4
	v_mad_i64_i32 v[20:21], s[56:57], s3, v218, v[76:77]
	global_load_dwordx4 v[20:23], v[20:21], off nt
.LBB0_1144:
	s_or_b64 exec, exec, s[46:47]
	v_mov_b64_e32 v[30:31], v[2:3]
	v_mov_b64_e32 v[28:29], v[0:1]
	s_and_saveexec_b64 s[46:47], vcc
	s_cbranch_execz .LBB0_1146
	s_or_b32 s3, s2, 5
	v_mad_i64_i32 v[2:3], s[56:57], s3, v218, v[76:77]
	global_load_dwordx4 v[28:31], v[2:3], off nt
.LBB0_1146:
	s_or_b64 exec, exec, s[46:47]
	v_mov_b32_e32 v2, v0
	v_mov_b32_e32 v3, v0
	v_mov_b32_e32 v1, v0
	v_mov_b64_e32 v[26:27], v[2:3]
	v_mov_b64_e32 v[24:25], v[0:1]
	s_and_saveexec_b64 s[46:47], vcc
	s_cbranch_execz .LBB0_1148
	s_or_b32 s3, s2, 6
	v_mad_i64_i32 v[24:25], s[56:57], s3, v218, v[76:77]
	global_load_dwordx4 v[24:27], v[24:25], off nt
.LBB0_1148:
	s_or_b64 exec, exec, s[46:47]
	v_mov_b64_e32 v[34:35], v[2:3]
	v_mov_b64_e32 v[32:33], v[0:1]
	s_and_saveexec_b64 s[46:47], vcc
	s_cbranch_execz .LBB0_1150
	s_or_b32 s3, s2, 7
	v_mad_i64_i32 v[2:3], s[56:57], s3, v218, v[76:77]
	global_load_dwordx4 v[32:35], v[2:3], off nt
.LBB0_1150:
	s_or_b64 exec, exec, s[46:47]
	v_add_u32_e32 v1, 0x100, v36
	v_mov_b32_e32 v2, v0
	v_mov_b32_e32 v3, v0
	v_cmp_gt_i32_e32 vcc, s54, v1
	v_mov_b32_e32 v1, v0
	v_mov_b64_e32 v[38:39], v[2:3]
	v_mov_b64_e32 v[36:37], v[0:1]
	s_and_saveexec_b64 s[46:47], vcc
	s_cbranch_execz .LBB0_1152
	v_mad_i64_i32 v[36:37], s[56:57], s2, v218, v[76:77]
	global_load_dwordx4 v[36:39], v[36:37], off offset:1024 nt
.LBB0_1152:
	s_or_b64 exec, exec, s[46:47]
	v_mov_b64_e32 v[42:43], v[2:3]
	v_mov_b64_e32 v[40:41], v[0:1]
	s_and_saveexec_b64 s[46:47], vcc
	s_cbranch_execz .LBB0_1154
	s_or_b32 s3, s2, 1
	v_mad_i64_i32 v[2:3], s[56:57], s3, v218, v[76:77]
	global_load_dwordx4 v[40:43], v[2:3], off offset:1024 nt
.LBB0_1154:
	s_or_b64 exec, exec, s[46:47]
	v_mov_b32_e32 v2, v0
	v_mov_b32_e32 v3, v0
	v_mov_b32_e32 v1, v0
	v_mov_b64_e32 v[46:47], v[2:3]
	v_mov_b64_e32 v[44:45], v[0:1]
	s_and_saveexec_b64 s[46:47], vcc
	s_cbranch_execz .LBB0_1156
	s_or_b32 s3, s2, 2
	v_mad_i64_i32 v[44:45], s[56:57], s3, v218, v[76:77]
	global_load_dwordx4 v[44:47], v[44:45], off offset:1024 nt
.LBB0_1156:
	s_or_b64 exec, exec, s[46:47]
	v_mov_b64_e32 v[50:51], v[2:3]
	v_mov_b64_e32 v[48:49], v[0:1]
	s_and_saveexec_b64 s[46:47], vcc
	s_cbranch_execz .LBB0_1158
	s_or_b32 s3, s2, 3
	v_mad_i64_i32 v[2:3], s[56:57], s3, v218, v[76:77]
	global_load_dwordx4 v[48:51], v[2:3], off offset:1024 nt
.LBB0_1158:
	s_or_b64 exec, exec, s[46:47]
	v_mov_b32_e32 v2, v0
	v_mov_b32_e32 v3, v0
	v_mov_b32_e32 v1, v0
	v_mov_b64_e32 v[54:55], v[2:3]
	v_mov_b64_e32 v[52:53], v[0:1]
	s_and_saveexec_b64 s[46:47], vcc
	s_cbranch_execz .LBB0_1160
	s_or_b32 s3, s2, 4
	v_mad_i64_i32 v[52:53], s[56:57], s3, v218, v[76:77]
	global_load_dwordx4 v[52:55], v[52:53], off offset:1024 nt
.LBB0_1160:
	s_or_b64 exec, exec, s[46:47]
	v_mov_b64_e32 v[62:63], v[2:3]
	v_mov_b64_e32 v[60:61], v[0:1]
	s_and_saveexec_b64 s[46:47], vcc
	s_cbranch_execz .LBB0_1162
	s_or_b32 s3, s2, 5
	v_mad_i64_i32 v[2:3], s[56:57], s3, v218, v[76:77]
	global_load_dwordx4 v[60:63], v[2:3], off offset:1024 nt
.LBB0_1162:
	s_or_b64 exec, exec, s[46:47]
	v_mov_b32_e32 v2, v0
	v_mov_b32_e32 v3, v0
	v_mov_b32_e32 v1, v0
	v_mov_b64_e32 v[58:59], v[2:3]
	v_mov_b64_e32 v[56:57], v[0:1]
	s_and_saveexec_b64 s[46:47], vcc
	s_cbranch_execz .LBB0_1164
	s_or_b32 s3, s2, 6
	v_mad_i64_i32 v[56:57], s[56:57], s3, v218, v[76:77]
	global_load_dwordx4 v[56:59], v[56:57], off offset:1024 nt
.LBB0_1164:
	s_or_b64 exec, exec, s[46:47]
	v_mov_b64_e32 v[66:67], v[2:3]
	v_mov_b64_e32 v[64:65], v[0:1]
	s_and_saveexec_b64 s[46:47], vcc
	s_cbranch_execz .LBB0_1166
	s_or_b32 s3, s2, 7
	v_mad_i64_i32 v[2:3], s[56:57], s3, v218, v[76:77]
	global_load_dwordx4 v[64:67], v[2:3], off offset:1024 nt

; __device__ __forceinline__ void cvt_tile(const float* W, int ldw, int nvalid, int k0, int n0, bf16_t* WT, int K, int map, int rows_cap, LAS unsigned char* T, int tid, const float* gvec) {
;     const int lane = tid & 63, w = __builtin_amdgcn_readfirstlane(tid >> 6);
;     f32x4 v[2][8];
; #pragma unroll
;     for (int hh = 0; hh < 2; ++hh)
; #pragma unroll
;         for (int rr = 0; rr < 8; ++rr) { const int k = k0 + 8 * w + rr, nc = n0 + 256 * hh + 4 * lane;
;             v[hh][rr] = nc < nvalid ? *(const f32x4*)(W + (size_t)k * ldw + nc) : (f32x4){0.f, 0.f, 0.f, 0.f}; }
.LBB0_1187:
	s_mul_hi_i32 s2, s47, 0x2e8ba2e9
	s_lshr_b32 s3, s2, 31
	s_ashr_i32 s2, s2, 1
	s_add_i32 s42, s2, s3
	s_mul_i32 s3, s42, 0xffffea00
	v_readfirstlane_b32 s43, v194
	s_add_i32 s3, s3, s49
	s_ashr_i32 s51, s43, 6
	v_add_u32_e32 v36, s3, v78
	v_mov_b32_e32 v2, v0
	v_mov_b32_e32 v3, v0
	s_lshl_b32 s2, s42, 6
	s_lshl_b32 s3, s51, 3
	v_ashrrev_i32_e32 v37, 31, v36
	v_mov_b32_e32 v1, v0
	v_mov_b64_e32 v[6:7], v[2:3]
	s_add_i32 s2, s3, s2
	v_cmp_gt_i32_e32 vcc, s54, v36
	v_lshl_add_u64 v[76:77], v[36:37], 2, s[26:27]
	v_mov_b64_e32 v[4:5], v[0:1]
	s_and_saveexec_b64 s[44:45], vcc
	s_cbranch_execz .LBB0_1189
	v_mad_i64_i32 v[4:5], s[52:53], s2, v218, v[76:77]
	global_load_dwordx4 v[4:7], v[4:5], off nt
.LBB0_1189:
	s_or_b64 exec, exec, s[44:45]
	v_mov_b64_e32 v[10:11], v[2:3]
	v_mov_b64_e32 v[8:9], v[0:1]
	s_and_saveexec_b64 s[44:45], vcc
	s_cbranch_execz .LBB0_1191
	s_or_b32 s3, s2, 1
	v_mad_i64_i32 v[2:3], s[52:53], s3, v218, v[76:77]
	global_load_dwordx4 v[8:11], v[2:3], off nt
.LBB0_1191:
	s_or_b64 exec, exec, s[44:45]
	v_mov_b32_e32 v2, v0
	v_mov_b32_e32 v3, v0
	v_mov_b32_e32 v1, v0
	v_mov_b64_e32 v[14:15], v[2:3]
	v_mov_b64_e32 v[12:13], v[0:1]
	s_and_saveexec_b64 s[44:45], vcc
	s_cbranch_execz .LBB0_1193
	s_or_b32 s3, s2, 2
	v_mad_i64_i32 v[12:13], s[52:53], s3, v218, v[76:77]
	global_load_dwordx4 v[12:15], v[12:13], off nt
.LBB0_1193:
	s_or_b64 exec, exec, s[44:45]
	v_mov_b64_e32 v[18:19], v[2:3]
	v_mov_b64_e32 v[16:17], v[0:1]
	s_and_saveexec_b64 s[44:45], vcc
	s_cbranch_execz .LBB0_1195
	s_or_b32 s3, s2, 3
	v_mad_i64_i32 v[2:3], s[52:53], s3, v218, v[76:77]
	global_load_dwordx4 v[16:19], v[2:3], off nt
.LBB0_1195:
	s_or_b64 exec, exec, s[44:45]
	v_mov_b32_e32 v2, v0
	v_mov_b32_e32 v3, v0
	v_mov_b32_e32 v1, v0
	v_mov_b64_e32 v[22:23], v[2:3]
	v_mov_b64_e32 v[20:21], v[0:1]
	s_and_saveexec_b64 s[44:45], vcc
	s_cbranch_execz .LBB0_1197
	s_or_b32 s3, s2, 4
	v_mad_i64_i32 v[20:21], s[52:53], s3, v218, v[76:77]
	global_load_dwordx4 v[20:23], v[20:21], off nt
.LBB0_1197:
	s_or_b64 exec, exec, s[44:45]
	v_mov_b64_e32 v[30:31], v[2:3]
	v_mov_b64_e32 v[28:29], v[0:1]
	s_and_saveexec_b64 s[44:45], vcc
	s_cbranch_execz .LBB0_1199
	s_or_b32 s3, s2, 5
	v_mad_i64_i32 v[2:3], s[52:53], s3, v218, v[76:77]
	global_load_dwordx4 v[28:31], v[2:3], off nt
.LBB0_1199:
	s_or_b64 exec, exec, s[44:45]
	v_mov_b32_e32 v2, v0
	v_mov_b32_e32 v3, v0
	v_mov_b32_e32 v1, v0
	v_mov_b64_e32 v[26:27], v[2:3]
	v_mov_b64_e32 v[24:25], v[0:1]
	s_and_saveexec_b64 s[44:45], vcc
	s_cbranch_execz .LBB0_1201
	s_or_b32 s3, s2, 6
	v_mad_i64_i32 v[24:25], s[52:53], s3, v218, v[76:77]
	global_load_dwordx4 v[24:27], v[24:25], off nt
.LBB0_1201:
	s_or_b64 exec, exec, s[44:45]
	v_mov_b64_e32 v[34:35], v[2:3]
	v_mov_b64_e32 v[32:33], v[0:1]
	s_and_saveexec_b64 s[44:45], vcc
	s_cbranch_execz .LBB0_1203
	s_or_b32 s3, s2, 7
	v_mad_i64_i32 v[2:3], s[52:53], s3, v218, v[76:77]
	global_load_dwordx4 v[32:35], v[2:3], off nt
.LBB0_1203:
	s_or_b64 exec, exec, s[44:45]
	v_add_u32_e32 v1, 0x100, v36
	v_mov_b32_e32 v2, v0
	v_mov_b32_e32 v3, v0
	v_cmp_gt_i32_e32 vcc, s54, v1
	v_mov_b32_e32 v1, v0
	v_mov_b64_e32 v[38:39], v[2:3]
	v_mov_b64_e32 v[36:37], v[0:1]
	s_and_saveexec_b64 s[44:45], vcc
	s_cbranch_execz .LBB0_1205
	v_mad_i64_i32 v[36:37], s[52:53], s2, v218, v[76:77]
	global_load_dwordx4 v[36:39], v[36:37], off offset:1024 nt
.LBB0_1205:
	s_or_b64 exec, exec, s[44:45]
	v_mov_b64_e32 v[42:43], v[2:3]
	v_mov_b64_e32 v[40:41], v[0:1]
	s_and_saveexec_b64 s[44:45], vcc
	s_cbranch_execz .LBB0_1207
	s_or_b32 s3, s2, 1
	v_mad_i64_i32 v[2:3], s[52:53], s3, v218, v[76:77]
	global_load_dwordx4 v[40:43], v[2:3], off offset:1024 nt
.LBB0_1207:
	s_or_b64 exec, exec, s[44:45]
	v_mov_b32_e32 v2, v0
	v_mov_b32_e32 v3, v0
	v_mov_b32_e32 v1, v0
	v_mov_b64_e32 v[46:47], v[2:3]
	v_mov_b64_e32 v[44:45], v[0:1]
	s_and_saveexec_b64 s[44:45], vcc
	s_cbranch_execz .LBB0_1209
	s_or_b32 s3, s2, 2
	v_mad_i64_i32 v[44:45], s[52:53], s3, v218, v[76:77]
	global_load_dwordx4 v[44:47], v[44:45], off offset:1024 nt
.LBB0_1209:
	s_or_b64 exec, exec, s[44:45]
	v_mov_b64_e32 v[50:51], v[2:3]
	v_mov_b64_e32 v[48:49], v[0:1]
	s_and_saveexec_b64 s[44:45], vcc
	s_cbranch_execz .LBB0_1211
	s_or_b32 s3, s2, 3
	v_mad_i64_i32 v[2:3], s[52:53], s3, v218, v[76:77]
	global_load_dwordx4 v[48:51], v[2:3], off offset:1024 nt
.LBB0_1211:
	s_or_b64 exec, exec, s[44:45]
	v_mov_b32_e32 v2, v0
	v_mov_b32_e32 v3, v0
	v_mov_b32_e32 v1, v0
	v_mov_b64_e32 v[54:55], v[2:3]
	v_mov_b64_e32 v[52:53], v[0:1]
	s_and_saveexec_b64 s[44:45], vcc
	s_cbranch_execz .LBB0_1213
	s_or_b32 s3, s2, 4
	v_mad_i64_i32 v[52:53], s[52:53], s3, v218, v[76:77]
	global_load_dwordx4 v[52:55], v[52:53], off offset:1024 nt
.LBB0_1213:
	s_or_b64 exec, exec, s[44:45]
	v_mov_b64_e32 v[62:63], v[2:3]
	v_mov_b64_e32 v[60:61], v[0:1]
	s_and_saveexec_b64 s[44:45], vcc
	s_cbranch_execz .LBB0_1215
	s_or_b32 s3, s2, 5
	v_mad_i64_i32 v[2:3], s[52:53], s3, v218, v[76:77]
	global_load_dwordx4 v[60:63], v[2:3], off offset:1024 nt
.LBB0_1215:
	s_or_b64 exec, exec, s[44:45]
	v_mov_b32_e32 v2, v0
	v_mov_b32_e32 v3, v0
	v_mov_b32_e32 v1, v0
	v_mov_b64_e32 v[58:59], v[2:3]
	v_mov_b64_e32 v[56:57], v[0:1]
	s_and_saveexec_b64 s[44:45], vcc
	s_cbranch_execz .LBB0_1217
	s_or_b32 s3, s2, 6
	v_mad_i64_i32 v[56:57], s[52:53], s3, v218, v[76:77]
	global_load_dwordx4 v[56:59], v[56:57], off offset:1024 nt
.LBB0_1217:
	s_or_b64 exec, exec, s[44:45]
	v_mov_b64_e32 v[66:67], v[2:3]
	v_mov_b64_e32 v[64:65], v[0:1]
	s_and_saveexec_b64 s[44:45], vcc
	s_cbranch_execz .LBB0_1219
	s_or_b32 s3, s2, 7
	v_mad_i64_i32 v[2:3], s[52:53], s3, v218, v[76:77]
	global_load_dwordx4 v[64:67], v[2:3], off offset:1024 nt

; __device__ __forceinline__ void cvt_tile(const float* W, int ldw, int nvalid, int k0, int n0, bf16_t* WT, int K, int map, int rows_cap, LAS unsigned char* T, int tid, const float* gvec) {
;     const int lane = tid & 63, w = __builtin_amdgcn_readfirstlane(tid >> 6);
;     f32x4 v[2][8];
; #pragma unroll
;     for (int hh = 0; hh < 2; ++hh)
; #pragma unroll
;         for (int rr = 0; rr < 8; ++rr) { const int k = k0 + 8 * w + rr, nc = n0 + 256 * hh + 4 * lane;
;             v[hh][rr] = nc < nvalid ? *(const f32x4*)(W + (size_t)k * ldw + nc) : (f32x4){0.f, 0.f, 0.f, 0.f}; }
.LBB0_1240:
	s_ashr_i32 s2, s46, 31
	s_lshr_b32 s2, s2, 30
	s_add_i32 s2, s46, s2
	s_ashr_i32 s42, s2, 2
	v_readfirstlane_b32 s43, v194
	v_add_u32_e32 v1, s5, v78
	s_lshl_b32 s38, s42, 11
	s_ashr_i32 s47, s43, 6
	v_subrev_u32_e32 v34, s38, v1
	s_lshl_b32 s2, s42, 6
	s_lshl_b32 s3, s47, 3
	v_ashrrev_i32_e32 v35, 31, v34
	s_add_i32 s44, s3, s2
	v_cmp_gt_i32_e32 vcc, s72, v34
	v_lshl_add_u64 v[66:67], v[34:35], 2, s[26:27]
	v_mov_b32_e32 v6, 0
	v_mov_b32_e32 v2, 0
	v_mov_b32_e32 v3, 0
	v_mov_b32_e32 v4, 0
	v_mov_b32_e32 v5, 0
	s_and_saveexec_b64 s[2:3], vcc
	s_cbranch_execz .LBB0_1242
	s_ashr_i32 s45, s44, 31
	s_lshl_b64 s[48:49], s[44:45], 13
	v_lshl_add_u64 v[2:3], v[66:67], 0, s[48:49]
	global_load_dwordx4 v[2:5], v[2:3], off nt
.LBB0_1242:
	s_or_b64 exec, exec, s[2:3]
	v_mov_b32_e32 v7, 0
	v_mov_b32_e32 v8, 0
	v_mov_b32_e32 v9, 0
	s_and_saveexec_b64 s[2:3], vcc
	s_cbranch_execz .LBB0_1244
	s_or_b32 s48, s44, 1
	s_ashr_i32 s49, s48, 31
	s_lshl_b64 s[48:49], s[48:49], 13
	v_lshl_add_u64 v[6:7], v[66:67], 0, s[48:49]
	global_load_dwordx4 v[6:9], v[6:7], off nt
.LBB0_1244:
	s_or_b64 exec, exec, s[2:3]
	v_mov_b32_e32 v10, 0
	v_mov_b32_e32 v14, 0
	v_mov_b32_e32 v15, 0
	v_mov_b32_e32 v16, 0
	v_mov_b32_e32 v17, 0
	s_and_saveexec_b64 s[2:3], vcc
	s_cbranch_execz .LBB0_1246
	s_or_b32 s48, s44, 2
	s_ashr_i32 s49, s48, 31
	s_lshl_b64 s[48:49], s[48:49], 13
	v_lshl_add_u64 v[12:13], v[66:67], 0, s[48:49]
	global_load_dwordx4 v[14:17], v[12:13], off nt
.LBB0_1246:
	s_or_b64 exec, exec, s[2:3]
	v_mov_b32_e32 v11, 0
	v_mov_b32_e32 v12, 0
	v_mov_b32_e32 v13, 0
	s_and_saveexec_b64 s[2:3], vcc
	s_cbranch_execz .LBB0_1248
	s_or_b32 s48, s44, 3
	s_ashr_i32 s49, s48, 31
	s_lshl_b64 s[48:49], s[48:49], 13
	v_lshl_add_u64 v[10:11], v[66:67], 0, s[48:49]
	global_load_dwordx4 v[10:13], v[10:11], off nt
.LBB0_1248:
	s_or_b64 exec, exec, s[2:3]
	v_mov_b32_e32 v18, 0
	v_mov_b32_e32 v22, 0
	v_mov_b32_e32 v23, 0
	v_mov_b32_e32 v24, 0
	v_mov_b32_e32 v25, 0
	s_and_saveexec_b64 s[2:3], vcc
	s_cbranch_execz .LBB0_1250
	s_or_b32 s48, s44, 4
	s_ashr_i32 s49, s48, 31
	s_lshl_b64 s[48:49], s[48:49], 13
	v_lshl_add_u64 v[20:21], v[66:67], 0, s[48:49]
	global_load_dwordx4 v[22:25], v[20:21], off nt
.LBB0_1250:
	s_or_b64 exec, exec, s[2:3]
	v_mov_b32_e32 v19, 0
	v_mov_b32_e32 v20, 0
	v_mov_b32_e32 v21, 0
	s_and_saveexec_b64 s[2:3], vcc
	s_cbranch_execz .LBB0_1252
	s_or_b32 s48, s44, 5
	s_ashr_i32 s49, s48, 31
	s_lshl_b64 s[48:49], s[48:49], 13
	v_lshl_add_u64 v[18:19], v[66:67], 0, s[48:49]
	global_load_dwordx4 v[18:21], v[18:19], off nt
.LBB0_1252:
	s_or_b64 exec, exec, s[2:3]
	v_mov_b32_e32 v26, 0
	v_mov_b32_e32 v30, 0
	v_mov_b32_e32 v31, 0
	v_mov_b32_e32 v32, 0
	v_mov_b32_e32 v33, 0
	s_and_saveexec_b64 s[2:3], vcc
	s_cbranch_execz .LBB0_1254
	s_or_b32 s48, s44, 6
	s_ashr_i32 s49, s48, 31
	s_lshl_b64 s[48:49], s[48:49], 13
	v_lshl_add_u64 v[28:29], v[66:67], 0, s[48:49]
	global_load_dwordx4 v[30:33], v[28:29], off nt
.LBB0_1254:
	s_or_b64 exec, exec, s[2:3]
	v_mov_b32_e32 v27, 0
	v_mov_b32_e32 v28, 0
	v_mov_b32_e32 v29, 0
	s_and_saveexec_b64 s[2:3], vcc
	s_cbranch_execz .LBB0_1256
	s_or_b32 s48, s44, 7
	s_ashr_i32 s49, s48, 31
	s_lshl_b64 s[48:49], s[48:49], 13
	v_lshl_add_u64 v[26:27], v[66:67], 0, s[48:49]
	global_load_dwordx4 v[26:29], v[26:27], off nt
.LBB0_1256:
	s_or_b64 exec, exec, s[2:3]
	v_add_u32_e32 v1, 0x100, v34
	v_cmp_gt_i32_e32 vcc, s72, v1
	v_mov_b32_e32 v38, 0
	v_mov_b32_e32 v34, 0
	v_mov_b32_e32 v35, 0
	v_mov_b32_e32 v36, 0
	v_mov_b32_e32 v37, 0
	s_and_saveexec_b64 s[2:3], vcc
	s_cbranch_execz .LBB0_1258
	s_ashr_i32 s45, s44, 31
	s_lshl_b64 s[48:49], s[44:45], 13
	v_lshl_add_u64 v[34:35], v[66:67], 0, s[48:49]
	global_load_dwordx4 v[34:37], v[34:35], off offset:1024 nt
.LBB0_1258:
	s_or_b64 exec, exec, s[2:3]
	v_mov_b32_e32 v39, 0
	v_mov_b32_e32 v40, 0
	v_mov_b32_e32 v41, 0
	s_and_saveexec_b64 s[2:3], vcc
	s_cbranch_execz .LBB0_1260
	s_or_b32 s48, s44, 1
	s_ashr_i32 s49, s48, 31
	s_lshl_b64 s[48:49], s[48:49], 13
	v_lshl_add_u64 v[38:39], v[66:67], 0, s[48:49]
	global_load_dwordx4 v[38:41], v[38:39], off offset:1024 nt
.LBB0_1260:
	s_or_b64 exec, exec, s[2:3]
	v_mov_b32_e32 v42, 0
	v_mov_b32_e32 v46, 0
	v_mov_b32_e32 v47, 0
	v_mov_b32_e32 v48, 0
	v_mov_b32_e32 v49, 0
	s_and_saveexec_b64 s[2:3], vcc
	s_cbranch_execz .LBB0_1262
	s_or_b32 s48, s44, 2
	s_ashr_i32 s49, s48, 31
	s_lshl_b64 s[48:49], s[48:49], 13
	v_lshl_add_u64 v[44:45], v[66:67], 0, s[48:49]
	global_load_dwordx4 v[46:49], v[44:45], off offset:1024 nt
.LBB0_1262:
	s_or_b64 exec, exec, s[2:3]
	v_mov_b32_e32 v43, 0
	v_mov_b32_e32 v44, 0
	v_mov_b32_e32 v45, 0
	s_and_saveexec_b64 s[2:3], vcc
	s_cbranch_execz .LBB0_1264
	s_or_b32 s48, s44, 3
	s_ashr_i32 s49, s48, 31
	s_lshl_b64 s[48:49], s[48:49], 13
	v_lshl_add_u64 v[42:43], v[66:67], 0, s[48:49]
	global_load_dwordx4 v[42:45], v[42:43], off offset:1024 nt
.LBB0_1264:
	s_or_b64 exec, exec, s[2:3]
	v_mov_b32_e32 v50, 0
	v_mov_b32_e32 v54, 0
	v_mov_b32_e32 v55, 0
	v_mov_b32_e32 v56, 0
	v_mov_b32_e32 v57, 0
	s_and_saveexec_b64 s[2:3], vcc
	s_cbranch_execz .LBB0_1266
	s_or_b32 s48, s44, 4
	s_ashr_i32 s49, s48, 31
	s_lshl_b64 s[48:49], s[48:49], 13
	v_lshl_add_u64 v[52:53], v[66:67], 0, s[48:49]
	global_load_dwordx4 v[54:57], v[52:53], off offset:1024 nt
.LBB0_1266:
	s_or_b64 exec, exec, s[2:3]
	v_mov_b32_e32 v51, 0
	v_mov_b32_e32 v52, 0
	v_mov_b32_e32 v53, 0
	s_and_saveexec_b64 s[2:3], vcc
	s_cbranch_execz .LBB0_1268
	s_or_b32 s48, s44, 5
	s_ashr_i32 s49, s48, 31
	s_lshl_b64 s[48:49], s[48:49], 13
	v_lshl_add_u64 v[50:51], v[66:67], 0, s[48:49]
	global_load_dwordx4 v[50:53], v[50:51], off offset:1024 nt
.LBB0_1268:
	s_or_b64 exec, exec, s[2:3]
	v_mov_b32_e32 v58, 0
	v_mov_b32_e32 v62, 0
	v_mov_b32_e32 v63, 0
	v_mov_b32_e32 v64, 0
	v_mov_b32_e32 v65, 0
	s_and_saveexec_b64 s[2:3], vcc
	s_cbranch_execz .LBB0_1270
	s_or_b32 s48, s44, 6
	s_ashr_i32 s49, s48, 31
	s_lshl_b64 s[48:49], s[48:49], 13
	v_lshl_add_u64 v[60:61], v[66:67], 0, s[48:49]
	global_load_dwordx4 v[62:65], v[60:61], off offset:1024 nt
.LBB0_1270:
	s_or_b64 exec, exec, s[2:3]
	v_mov_b32_e32 v59, 0
	v_mov_b32_e32 v60, 0
	v_mov_b32_e32 v61, 0
	s_and_saveexec_b64 s[2:3], vcc
	s_cbranch_execz .LBB0_1272
	s_or_b32 s44, s44, 7
	s_ashr_i32 s45, s44, 31
	s_lshl_b64 s[44:45], s[44:45], 13
	v_lshl_add_u64 v[58:59], v[66:67], 0, s[44:45]
	global_load_dwordx4 v[58:61], v[58:59], off offset:1024 nt

; __device__ __forceinline__ void cvt_tile(const float* W, int ldw, int nvalid, int k0, int n0, bf16_t* WT, int K, int map, int rows_cap, LAS unsigned char* T, int tid, const float* gvec) {
;     const int lane = tid & 63, w = __builtin_amdgcn_readfirstlane(tid >> 6);
;     f32x4 v[2][8];
; #pragma unroll
;     for (int hh = 0; hh < 2; ++hh)
; #pragma unroll
;         for (int rr = 0; rr < 8; ++rr) { const int k = k0 + 8 * w + rr, nc = n0 + 256 * hh + 4 * lane;
;             v[hh][rr] = nc < nvalid ? *(const f32x4*)(W + (size_t)k * ldw + nc) : (f32x4){0.f, 0.f, 0.f, 0.f}; }
.LBB0_1359:
	s_mul_hi_i32 s2, s5, 0x66666667
	s_lshr_b32 s3, s2, 31
	s_ashr_i32 s2, s2, 2
	s_add_i32 s14, s2, s3
	s_mul_i32 s3, s14, 0xffffec00
	v_readfirstlane_b32 s15, v194
	s_add_i32 s3, s3, s0
	s_ashr_i32 s18, s15, 6
	v_add_u32_e32 v36, s3, v82
	v_mov_b32_e32 v2, v0
	v_mov_b32_e32 v3, v0
	s_lshl_b32 s2, s14, 6
	s_lshl_b32 s3, s18, 3
	v_ashrrev_i32_e32 v37, 31, v36
	v_mov_b32_e32 v1, v0
	v_mov_b64_e32 v[6:7], v[2:3]
	s_add_i32 s2, s3, s2
	v_cmp_gt_i32_e32 vcc, s25, v36
	v_lshl_add_u64 v[70:71], v[36:37], 2, s[10:11]
	v_mov_b64_e32 v[4:5], v[0:1]
	s_and_saveexec_b64 s[16:17], vcc
	s_cbranch_execz .LBB0_1361
	v_mad_i64_i32 v[4:5], s[20:21], s2, v213, v[70:71]
	global_load_dwordx4 v[4:7], v[4:5], off nt
.LBB0_1361:
	s_or_b64 exec, exec, s[16:17]
	v_mov_b64_e32 v[10:11], v[2:3]
	v_mov_b64_e32 v[8:9], v[0:1]
	s_and_saveexec_b64 s[16:17], vcc
	s_cbranch_execz .LBB0_1363
	s_or_b32 s3, s2, 1
	v_mad_i64_i32 v[2:3], s[20:21], s3, v213, v[70:71]
	global_load_dwordx4 v[8:11], v[2:3], off nt
.LBB0_1363:
	s_or_b64 exec, exec, s[16:17]
	v_mov_b32_e32 v2, v0
	v_mov_b32_e32 v3, v0
	v_mov_b32_e32 v1, v0
	v_mov_b64_e32 v[14:15], v[2:3]
	v_mov_b64_e32 v[12:13], v[0:1]
	s_and_saveexec_b64 s[16:17], vcc
	s_cbranch_execz .LBB0_1365
	s_or_b32 s3, s2, 2
	v_mad_i64_i32 v[12:13], s[20:21], s3, v213, v[70:71]
	global_load_dwordx4 v[12:15], v[12:13], off nt
.LBB0_1365:
	s_or_b64 exec, exec, s[16:17]
	v_mov_b64_e32 v[18:19], v[2:3]
	v_mov_b64_e32 v[16:17], v[0:1]
	s_and_saveexec_b64 s[16:17], vcc
	s_cbranch_execz .LBB0_1367
	s_or_b32 s3, s2, 3
	v_mad_i64_i32 v[2:3], s[20:21], s3, v213, v[70:71]
	global_load_dwordx4 v[16:19], v[2:3], off nt
.LBB0_1367:
	s_or_b64 exec, exec, s[16:17]
	v_mov_b32_e32 v2, v0
	v_mov_b32_e32 v3, v0
	v_mov_b32_e32 v1, v0
	v_mov_b64_e32 v[22:23], v[2:3]
	v_mov_b64_e32 v[20:21], v[0:1]
	s_and_saveexec_b64 s[16:17], vcc
	s_cbranch_execz .LBB0_1369
	s_or_b32 s3, s2, 4
	v_mad_i64_i32 v[20:21], s[20:21], s3, v213, v[70:71]
	global_load_dwordx4 v[20:23], v[20:21], off nt
.LBB0_1369:
	s_or_b64 exec, exec, s[16:17]
	v_mov_b64_e32 v[30:31], v[2:3]
	v_mov_b64_e32 v[28:29], v[0:1]
	s_and_saveexec_b64 s[16:17], vcc
	s_cbranch_execz .LBB0_1371
	s_or_b32 s3, s2, 5
	v_mad_i64_i32 v[2:3], s[20:21], s3, v213, v[70:71]
	global_load_dwordx4 v[28:31], v[2:3], off nt
.LBB0_1371:
	s_or_b64 exec, exec, s[16:17]
	v_mov_b32_e32 v2, v0
	v_mov_b32_e32 v3, v0
	v_mov_b32_e32 v1, v0
	v_mov_b64_e32 v[26:27], v[2:3]
	v_mov_b64_e32 v[24:25], v[0:1]
	s_and_saveexec_b64 s[16:17], vcc
	s_cbranch_execz .LBB0_1373
	s_or_b32 s3, s2, 6
	v_mad_i64_i32 v[24:25], s[20:21], s3, v213, v[70:71]
	global_load_dwordx4 v[24:27], v[24:25], off nt
.LBB0_1373:
	s_or_b64 exec, exec, s[16:17]
	v_mov_b64_e32 v[34:35], v[2:3]
	v_mov_b64_e32 v[32:33], v[0:1]
	s_and_saveexec_b64 s[16:17], vcc
	s_cbranch_execz .LBB0_1375
	s_or_b32 s3, s2, 7
	v_mad_i64_i32 v[2:3], s[20:21], s3, v213, v[70:71]
	global_load_dwordx4 v[32:35], v[2:3], off nt
.LBB0_1375:
	s_or_b64 exec, exec, s[16:17]
	v_add_u32_e32 v1, 0x100, v36
	v_mov_b32_e32 v2, v0
	v_mov_b32_e32 v3, v0
	v_cmp_gt_i32_e32 vcc, s25, v1
	v_mov_b32_e32 v1, v0
	v_mov_b64_e32 v[38:39], v[2:3]
	v_mov_b64_e32 v[36:37], v[0:1]
	s_and_saveexec_b64 s[16:17], vcc
	s_cbranch_execz .LBB0_1377
	v_mad_i64_i32 v[36:37], s[20:21], s2, v213, v[70:71]
	global_load_dwordx4 v[36:39], v[36:37], off offset:1024 nt
.LBB0_1377:
	s_or_b64 exec, exec, s[16:17]
	v_mov_b64_e32 v[42:43], v[2:3]
	v_mov_b64_e32 v[40:41], v[0:1]
	s_and_saveexec_b64 s[16:17], vcc
	s_cbranch_execz .LBB0_1379
	s_or_b32 s3, s2, 1
	v_mad_i64_i32 v[2:3], s[20:21], s3, v213, v[70:71]
	global_load_dwordx4 v[40:43], v[2:3], off offset:1024 nt
.LBB0_1379:
	s_or_b64 exec, exec, s[16:17]
	v_mov_b32_e32 v2, v0
	v_mov_b32_e32 v3, v0
	v_mov_b32_e32 v1, v0
	v_mov_b64_e32 v[46:47], v[2:3]
	v_mov_b64_e32 v[44:45], v[0:1]
	s_and_saveexec_b64 s[16:17], vcc
	s_cbranch_execz .LBB0_1381
	s_or_b32 s3, s2, 2
	v_mad_i64_i32 v[44:45], s[20:21], s3, v213, v[70:71]
	global_load_dwordx4 v[44:47], v[44:45], off offset:1024 nt
.LBB0_1381:
	s_or_b64 exec, exec, s[16:17]
	v_mov_b64_e32 v[50:51], v[2:3]
	v_mov_b64_e32 v[48:49], v[0:1]
	s_and_saveexec_b64 s[16:17], vcc
	s_cbranch_execz .LBB0_1383
	s_or_b32 s3, s2, 3
	v_mad_i64_i32 v[2:3], s[20:21], s3, v213, v[70:71]
	global_load_dwordx4 v[48:51], v[2:3], off offset:1024 nt
.LBB0_1383:
	s_or_b64 exec, exec, s[16:17]
	v_mov_b32_e32 v2, v0
	v_mov_b32_e32 v3, v0
	v_mov_b32_e32 v1, v0
	v_mov_b64_e32 v[54:55], v[2:3]
	v_mov_b64_e32 v[52:53], v[0:1]
	s_and_saveexec_b64 s[16:17], vcc
	s_cbranch_execz .LBB0_1385
	s_or_b32 s3, s2, 4
	v_mad_i64_i32 v[52:53], s[20:21], s3, v213, v[70:71]
	global_load_dwordx4 v[52:55], v[52:53], off offset:1024 nt
.LBB0_1385:
	s_or_b64 exec, exec, s[16:17]
	v_mov_b64_e32 v[62:63], v[2:3]
	v_mov_b64_e32 v[60:61], v[0:1]
	s_and_saveexec_b64 s[16:17], vcc
	s_cbranch_execz .LBB0_1387
	s_or_b32 s3, s2, 5
	v_mad_i64_i32 v[2:3], s[20:21], s3, v213, v[70:71]
	global_load_dwordx4 v[60:63], v[2:3], off offset:1024 nt
.LBB0_1387:
	s_or_b64 exec, exec, s[16:17]
	v_mov_b32_e32 v2, v0
	v_mov_b32_e32 v3, v0
	v_mov_b32_e32 v1, v0
	v_mov_b64_e32 v[58:59], v[2:3]
	v_mov_b64_e32 v[56:57], v[0:1]
	s_and_saveexec_b64 s[16:17], vcc
	s_cbranch_execz .LBB0_1389
	s_or_b32 s3, s2, 6
	v_mad_i64_i32 v[56:57], s[20:21], s3, v213, v[70:71]
	global_load_dwordx4 v[56:59], v[56:57], off offset:1024 nt
.LBB0_1389:
	s_or_b64 exec, exec, s[16:17]
	v_mov_b64_e32 v[66:67], v[2:3]
	v_mov_b64_e32 v[64:65], v[0:1]
	s_and_saveexec_b64 s[16:17], vcc
	s_cbranch_execz .LBB0_1391
	s_or_b32 s3, s2, 7
	v_mad_i64_i32 v[2:3], s[20:21], s3, v213, v[70:71]
	global_load_dwordx4 v[64:67], v[2:3], off offset:1024 nt

; #define LAS __attribute__((address_space(3)))
; __device__ __forceinline__ unsigned cvt_pk_bf16(float lo, float hi) { f32x2 v = {lo, hi}; bf16x2_t b = __builtin_convertvector(v, bf16x2_t); return __builtin_bit_cast(unsigned, b); }
; __device__ __forceinline__ void cvt_tile(const float* W, int ldw, int nvalid, int k0, int n0, bf16_t* WT, int K, int map, int rows_cap, LAS unsigned char* T, int tid, const float* gvec) {
;     ...
;     for (int hh = 0; hh < 2; ++hh)
; #pragma unroll
;         for (int rr = 0; rr < 8; ++rr) { const int k = k0 + 8 * w + rr, nc = n0 + 256 * hh + 4 * lane;
;             v[hh][rr] = nc < nvalid ? *(const f32x4*)(W + (size_t)k * ldw + nc) : (f32x4){0.f, 0.f, 0.f, 0.f}; }
;     if (gvec) {
; #pragma unroll
;         for (int rr = 0; rr < 8; ++rr) { const float gk = gvec[k0 + 8 * w + rr]; v[0][rr] = v[0][rr] * gk; v[1][rr] = v[1][rr] * gk; } }
;     const int phys = w ^ (lane & 7);
; #pragma unroll
;     for (int hh = 0; hh < 2; ++hh)
; #pragma unroll
;         for (int r = 0; r < 4; ++r)
; #pragma unroll
;             for (int jn = 0; jn < 4; ++jn) *(LAS unsigned*)(T + (256 * hh + 4 * lane + jn) * 128 + phys * 16 + r * 4) = cvt_pk_bf16(v[hh][2 * r][jn], v[hh][2 * r + 1][jn]);
;     __syncthreads();
;     const int kt = k0 >> 6, nkt = K >> 6;
; #pragma unroll
;     for (int it = 0; it < 8; ++it) { const int n = 64 * w + 8 * it + (lane >> 3), c = lane & 7;
;         const u32x4 o = *(const LAS u32x4*)(T + n * 128 + ((c ^ ((n >> 2) & 7)) << 4));
;         const int ng = n0 + n; const int d = map == 0 ? ng : (ng / 128) * 256 + (ng % 128) + (map == 2 ? 128 : 0);
;         if (d < rows_cap) *(u32x4*)(WT + ((size_t)(d >> 8) * nkt + kt) * 16384 + (d & 255) * 64 + 8 * c) = o; }
.LBB0_1432:
	v_readfirstlane_b32 s7, v194
	s_ashr_i32 s10, s7, 6
	s_lshl_b32 s2, s10, 3
	s_add_i32 s2, s5, s2
	s_ashr_i32 s3, s2, 31
	s_lshl_b64 s[8:9], s[2:3], 10
	v_lshl_add_u64 v[14:15], v[6:7], 0, s[8:9]
	s_add_i32 s8, s2, 1
	s_ashr_i32 s9, s8, 31
	s_lshl_b64 s[8:9], s[8:9], 10
	v_lshl_add_u64 v[18:19], v[6:7], 0, s[8:9]
	s_add_i32 s8, s2, 2
	s_ashr_i32 s9, s8, 31
	s_lshl_b64 s[8:9], s[8:9], 10
	v_lshl_add_u64 v[22:23], v[6:7], 0, s[8:9]
	s_add_i32 s8, s2, 3
	s_ashr_i32 s9, s8, 31
	global_load_dwordx4 v[14:17], v[14:15], off nt
	s_lshl_b64 s[8:9], s[8:9], 10
	global_load_dwordx4 v[18:21], v[18:19], off nt
	v_lshl_add_u64 v[26:27], v[6:7], 0, s[8:9]
	s_add_i32 s8, s2, 4
	s_ashr_i32 s9, s8, 31
	s_lshl_b64 s[8:9], s[8:9], 10
	global_load_dwordx4 v[22:25], v[22:23], off nt
	v_lshl_add_u64 v[30:31], v[6:7], 0, s[8:9]
	global_load_dwordx4 v[26:29], v[26:27], off nt
	s_add_i32 s8, s2, 5
	s_ashr_i32 s9, s8, 31
	s_lshl_b64 s[8:9], s[8:9], 10
	v_lshl_add_u64 v[34:35], v[6:7], 0, s[8:9]
	global_load_dwordx4 v[30:33], v[30:31], off nt
	s_add_i32 s8, s2, 6
	global_load_dwordx4 v[34:37], v[34:35], off nt
	s_add_i32 s2, s2, 7
	s_ashr_i32 s9, s8, 31
	s_ashr_i32 s3, s2, 31
	s_lshl_b64 s[8:9], s[8:9], 10
	s_lshl_b64 s[2:3], s[2:3], 10
	v_lshl_add_u64 v[38:39], v[6:7], 0, s[8:9]
	v_lshl_add_u64 v[42:43], v[6:7], 0, s[2:3]
	global_load_dwordx4 v[38:41], v[38:39], off nt
	v_xor_b32_e32 v46, s10, v1
	global_load_dwordx4 v[42:45], v[42:43], off nt
	v_lshl_add_u32 v46, v46, 4, 0
	s_and_b32 s2, s7, 0xffffffc0
	s_waitcnt vmcnt(0)
	v_cvt_pk_bf16_f32 v14, v14, v18
	v_add_u32_e32 v18, v46, v10
	ds_write_b32 v18, v14
	v_cvt_pk_bf16_f32 v14, v15, v19
	v_add_u32_e32 v15, v46, v72
	ds_write_b32 v15, v14
	v_cvt_pk_bf16_f32 v14, v16, v20
	v_add_u32_e32 v16, v46, v73
	ds_write_b32 v16, v14
	v_cvt_pk_bf16_f32 v14, v17, v21
	v_add_u32_e32 v17, v46, v74
	ds_write_b32 v17, v14
	v_cvt_pk_bf16_f32 v14, v22, v26
	ds_write_b32 v18, v14 offset:4
	v_cvt_pk_bf16_f32 v14, v23, v27
	ds_write_b32 v15, v14 offset:4
	v_cvt_pk_bf16_f32 v14, v24, v28
	ds_write_b32 v16, v14 offset:4
	v_cvt_pk_bf16_f32 v14, v25, v29
	ds_write_b32 v17, v14 offset:4
	v_cvt_pk_bf16_f32 v14, v30, v34
	ds_write_b32 v18, v14 offset:8
	v_cvt_pk_bf16_f32 v14, v31, v35
	ds_write_b32 v15, v14 offset:8
	v_cvt_pk_bf16_f32 v14, v32, v36
	ds_write_b32 v16, v14 offset:8
	v_cvt_pk_bf16_f32 v14, v33, v37
	ds_write_b32 v17, v14 offset:8
	v_cvt_pk_bf16_f32 v14, v38, v42
	ds_write_b32 v18, v14 offset:12
	v_cvt_pk_bf16_f32 v14, v39, v43
	ds_write_b32 v15, v14 offset:12
	v_cvt_pk_bf16_f32 v14, v40, v44
	ds_write_b32 v16, v14 offset:12
	v_cvt_pk_bf16_f32 v14, v41, v45
	ds_write_b32 v17, v14 offset:12
	v_add_u32_e32 v14, v46, v75
	v_add_u32_e32 v15, v46, v76
	v_add_u32_e32 v16, v46, v77
	v_add_u32_e32 v17, v46, v78
	ds_write_b32 v14, v0
	ds_write_b32 v15, v0
	ds_write_b32 v16, v0
	ds_write_b32 v17, v0
	ds_write_b32 v14, v0 offset:4
	ds_write_b32 v15, v0 offset:4
	ds_write_b32 v16, v0 offset:4
	ds_write_b32 v17, v0 offset:4
	ds_write_b32 v14, v0 offset:8
	ds_write_b32 v15, v0 offset:8
	ds_write_b32 v16, v0 offset:8
	ds_write_b32 v17, v0 offset:8
	ds_write_b32 v14, v0 offset:12
	ds_write_b32 v15, v0 offset:12
	ds_write_b32 v16, v0 offset:12
	ds_write_b32 v17, v0 offset:12
	v_or_b32_e32 v14, s2, v11
	v_cmp_gt_i32_e32 vcc, s73, v14
	s_waitcnt lgkmcnt(0)
	s_barrier
	s_and_saveexec_b64 s[2:3], vcc
	s_cbranch_execz .LBB0_1434
	v_lshlrev_b32_e32 v15, 7, v14
	v_add_u32_e32 v16, v12, v15
	ds_read_b128 v[16:19], v16
	s_ashr_i32 s8, s7, 8
	s_ashr_i32 s9, s8, 31
	s_lshl_b64 s[8:9], s[8:9], 17
	v_and_b32_e32 v15, 0x6380, v15
	v_or_b32_e32 v20, s8, v15
	v_mov_b32_e32 v21, s9
	v_lshl_add_u64 v[20:21], v[8:9], 0, v[20:21]
	s_waitcnt lgkmcnt(0)
	global_store_dwordx4 v[20:21], v[16:19], off

; __device__ __forceinline__ unsigned cvt_pk_bf16(float lo, float hi) { f32x2 v = {lo, hi}; bf16x2_t b = __builtin_convertvector(v, bf16x2_t); return __builtin_bit_cast(unsigned, b); }
; __device__ __forceinline__ void xb_rows(const float* X, bf16_t* out, float* ssq, int nrows, int gw, int ngw, int lane) {
;     for (int row = gw; row < nrows; row += ngw) {
;         const f32x4* xr = (const f32x4*)(X + (size_t)row * DM) + lane; float ss = 0.f;
; #pragma unroll
;         for (int j = 0; j < 8; ++j) { const f32x4 v = xr[64 * j]; ss += (v[0] * v[0] + v[1] * v[1]) + (v[2] * v[2] + v[3] * v[3]);
;             u32x2 w; w.x = cvt_pk_bf16(v[0], v[1]); w.y = cvt_pk_bf16(v[2], v[3]); ((u32x2*)(out + (size_t)row * DM))[lane + 64 * j] = w; }
;         ss = wave_sum(ss);
;         if (lane == 0) ssq[row] = ss;
;     }
; }
.LBB0_1453:
	global_load_dwordx4 v[84:87], v[6:7], off offset:-4096 nt
	global_load_dwordx4 v[88:91], v[6:7], off offset:-3072 nt
	global_load_dwordx4 v[92:95], v[6:7], off offset:-2048 nt
	global_load_dwordx4 v[96:99], v[6:7], off offset:-1024 nt
	global_load_dwordx4 v[100:103], v[6:7], off nt
	global_load_dwordx4 v[104:107], v[6:7], off offset:1024 nt
	global_load_dwordx4 v[108:111], v[6:7], off offset:2048 nt
	global_load_dwordx4 v[112:115], v[6:7], off offset:3072 nt
	s_mov_b32 s2, 0x11e00000
	v_lshl_add_u64 v[8:9], s[30:31], 0, v[4:5]
	s_waitcnt lgkmcnt(0)
	v_add_co_u32_e32 v8, vcc, s2, v8
	s_nop 1
	v_addc_co_u32_e32 v9, vcc, 0, v9, vcc
	s_waitcnt vmcnt(7)
	v_mul_f32_e32 v20, v85, v85
	v_mul_f32_e32 v22, v87, v87
	v_fmac_f32_e32 v20, v84, v84
	v_fmac_f32_e32 v22, v86, v86
	v_add_f32_e32 v20, v20, v22
	v_cvt_pk_bf16_f32 v16, v84, v85
	v_cvt_pk_bf16_f32 v17, v86, v87
	global_store_dwordx2 v[8:9], v[16:17], off
	s_waitcnt vmcnt(7)
	v_mul_f32_e32 v21, v89, v89
	v_mul_f32_e32 v22, v91, v91
	v_fmac_f32_e32 v21, v88, v88
	v_fmac_f32_e32 v22, v90, v90
	v_add_f32_e32 v21, v21, v22
	v_add_f32_e32 v20, v20, v21
	v_cvt_pk_bf16_f32 v16, v88, v89
	v_cvt_pk_bf16_f32 v17, v90, v91
	global_store_dwordx2 v[8:9], v[16:17], off offset:512
	s_waitcnt vmcnt(7)
	v_mul_f32_e32 v21, v93, v93
	v_mul_f32_e32 v22, v95, v95
	v_fmac_f32_e32 v21, v92, v92
	v_fmac_f32_e32 v22, v94, v94
	v_add_f32_e32 v21, v21, v22
	v_add_f32_e32 v20, v20, v21
	v_cvt_pk_bf16_f32 v16, v92, v93
	v_cvt_pk_bf16_f32 v17, v94, v95
	global_store_dwordx2 v[8:9], v[16:17], off offset:1024
	s_waitcnt vmcnt(7)
	v_mul_f32_e32 v21, v97, v97
	v_mul_f32_e32 v22, v99, v99
	v_fmac_f32_e32 v21, v96, v96
	v_fmac_f32_e32 v22, v98, v98
	v_add_f32_e32 v21, v21, v22
	v_add_f32_e32 v20, v20, v21
	v_cvt_pk_bf16_f32 v16, v96, v97
	v_cvt_pk_bf16_f32 v17, v98, v99
	global_store_dwordx2 v[8:9], v[16:17], off offset:1536
	s_waitcnt vmcnt(7)
	v_mul_f32_e32 v21, v101, v101
	v_mul_f32_e32 v22, v103, v103
	v_fmac_f32_e32 v21, v100, v100
	v_fmac_f32_e32 v22, v102, v102
	v_add_f32_e32 v21, v21, v22
	v_add_f32_e32 v20, v20, v21
	v_cvt_pk_bf16_f32 v16, v100, v101
	v_cvt_pk_bf16_f32 v17, v102, v103
	global_store_dwordx2 v[8:9], v[16:17], off offset:2048
	s_waitcnt vmcnt(7)
	v_mul_f32_e32 v21, v105, v105
	v_mul_f32_e32 v22, v107, v107
	v_fmac_f32_e32 v21, v104, v104
	v_fmac_f32_e32 v22, v106, v106
	v_add_f32_e32 v21, v21, v22
	v_add_f32_e32 v20, v20, v21
	v_cvt_pk_bf16_f32 v16, v104, v105
	v_cvt_pk_bf16_f32 v17, v106, v107
	global_store_dwordx2 v[8:9], v[16:17], off offset:2560
	s_waitcnt vmcnt(7)
	v_mul_f32_e32 v21, v109, v109
	v_mul_f32_e32 v22, v111, v111
	v_fmac_f32_e32 v21, v108, v108
	v_fmac_f32_e32 v22, v110, v110
	v_add_f32_e32 v21, v21, v22
	v_add_f32_e32 v20, v20, v21
	v_cvt_pk_bf16_f32 v16, v108, v109
	v_cvt_pk_bf16_f32 v17, v110, v111
	global_store_dwordx2 v[8:9], v[16:17], off offset:3072
	s_waitcnt vmcnt(7)
	v_mul_f32_e32 v21, v113, v113
	v_mul_f32_e32 v22, v115, v115
	v_fmac_f32_e32 v21, v112, v112
	v_fmac_f32_e32 v22, v114, v114
	v_add_f32_e32 v21, v21, v22
	v_add_f32_e32 v20, v20, v21
	v_cvt_pk_bf16_f32 v16, v112, v113
	v_cvt_pk_bf16_f32 v17, v114, v115
	global_store_dwordx2 v[8:9], v[16:17], off offset:3584
	ds_bpermute_b32 v8, v10, v20
	s_waitcnt lgkmcnt(0)
	v_add_f32_e32 v8, v20, v8
	ds_bpermute_b32 v9, v11, v8
	s_waitcnt lgkmcnt(0)
	v_add_f32_e32 v8, v8, v9
	ds_bpermute_b32 v9, v12, v8
	s_waitcnt lgkmcnt(0)
	v_add_f32_e32 v8, v8, v9
	ds_bpermute_b32 v9, v13, v8
	s_waitcnt lgkmcnt(0)
	v_add_f32_e32 v8, v8, v9
	ds_bpermute_b32 v9, v14, v8
	s_waitcnt lgkmcnt(0)
	v_add_f32_e32 v8, v8, v9
	ds_bpermute_b32 v9, v15, v8
	s_and_saveexec_b64 s[2:3], s[6:7]
	s_cbranch_execz .LBB0_1452
	s_add_u32 s10, s30, s0
	s_waitcnt lgkmcnt(0)
	v_add_f32_e32 v8, v8, v9
	s_addc_u32 s11, s31, s1
	global_store_dword v0, v8, s[10:11]
	s_branch .LBB0_1452
